# GEMM main loops: first iteration peeled, its k=0 MFMAs take inline 0 as accumulator input; the 128 accumulator-zeroing v_mov per tile prologue removed
# speedup vs baseline: 1.0049x; 1.0036x over previous
; #define LDA(dst, b, h) for (int m = 0; m < 4; ++m) for (int k = 0; k < 2; ++k) \
;     dst[m][k] = *reinterpret_cast<const bf16x8*>((char*)SA(b, h) + a_thr + (m * 2 + k) * 1024)
; #define LDB(dst, b, h) for (int n = 0; n < 2; ++n) for (int k = 0; k < 2; ++k) \
;     dst[n][k] = *reinterpret_cast<const bf16x8*>((char*)SB(b, h) + b_thr + (n * 2 + k) * 1024)
; #define MMA(ai, bj, At, Btf) do { __builtin_amdgcn_s_setprio(1); \
;     for (int m = 0; m < 4; ++m) for (int n = 0; n < 2; ++n) for (int k = 0; k < 2; ++k) \
;       acc[ai][bj][m][n] = __builtin_amdgcn_mfma_f32_16x16x32_bf16(Btf[n][k], At[m][k], acc[ai][bj][m][n], 0, 0, 0); \
;     __builtin_amdgcn_s_setprio(0); } while (0)
; #define WAIT_V(n) asm volatile("s_waitcnt vmcnt(" #n ")" ::: "memory")
; #define WAIT_L(n) asm volatile("s_waitcnt lgkmcnt(" #n ")" ::: "memory")
; #define BAR __builtin_amdgcn_s_barrier()
; #define SCHED __builtin_amdgcn_sched_barrier(0)
; template <bool OVL, bool PANEL = false, class Epi>
; __device__ __forceinline__ void gemm_phase(const bf16_t* __restrict__ A, long lda, const bf16_t* __restrict__ Bt, long ldb, int nM, int nN, int K,
;                                            const Epi& epi, bf16_t* shm, int w0) {
;     ...
;           for (int a3 = 0; a3 < 2; ++a3) acc[a0][a1][a2][a3] = (f32x4){0.f, 0.f, 0.f, 0.f};
;     bf16x8 At[4][2], B0[2][2], B1[2][2];
;     if (wr == 1) BAR;
;     WAIT_V(4); BAR;
;     STAGE(SB(1, 0), Bt, ldb, boff, bcol, 1); STAGE(SA(1, 0), A, lda, aoff, brow, 1); STAGE(SB(1, 1), Bt, ldb, boff, bcol + HALF, 1);
;     WAIT_V(6); BAR;
;     for (int t = 0; t < nt - 2; t += 2) {
;       LDB(B0, 0, 0); SCHED; LDA(At, 0, 0); STAGE(SA(1, 1), A, lda, aoff, brow + HALF, t + 1);
;       WAIT_L(8); BAR; WAIT_L(0); MMA(0, 0, At, B0); BAR; SCHED;
;       LDB(B1, 0, 1); STAGE(SB(0, 0), Bt, ldb, boff, bcol, t + 2);
.LBB0_124:
	s_or_b64 exec, exec, s[0:1]
	s_mul_i32 s2, s29, 0xb0000
	v_readlane_b32 s40, v251, 49
	s_lshl_b32 s28, s10, 8
	s_lshl_b64 s[0:1], s[2:3], 1
	v_readlane_b32 s42, v251, 51
	v_readlane_b32 s43, v251, 52
	s_add_u32 s0, s42, s0
	s_addc_u32 s1, s43, s1
	v_mov_b32_e32 v0, v203
	v_add_u32_e32 v130, s96, v202
	s_waitcnt vmcnt(4)
	s_barrier
	v_readlane_b32 s41, v251, 50
	v_readlane_b32 s44, v251, 53
	v_readlane_b32 s45, v251, 54
	v_readlane_b32 s46, v251, 55
	v_readlane_b32 s47, v251, 56
	s_mov_b64 s[6:7], 0x80
	v_lshl_add_u64 v[2:3], s[0:1], 0, v[0:1]
	v_readfirstlane_b32 s2, v130
	v_add_u32_e32 v131, 0x2000, v130
	v_lshl_add_u64 v[4:5], v[2:3], 0, s[6:7]
	s_mov_b32 m0, s2
	v_readfirstlane_b32 s2, v131
	v_readlane_b32 s40, v252, 20
	global_load_lds_dwordx4 v[4:5], off
	s_mov_b32 m0, s2
	s_mul_i32 s2, s10, 0x160000
	v_readlane_b32 s54, v252, 34
	s_mov_b64 s[8:9], 0x58080
	s_mul_hi_i32 s5, s28, 0x1600
	v_readlane_b32 s55, v252, 35
	s_add_u32 s4, s54, s2
	v_lshl_add_u64 v[2:3], v[2:3], 0, s[8:9]
	s_addc_u32 s5, s55, s5
	v_mov_b32_e32 v0, v203
	v_add_u32_e32 v132, 0x8000, v206
	global_load_lds_dwordx4 v[2:3], off
	v_readfirstlane_b32 s2, v132
	v_lshl_add_u64 v[2:3], s[4:5], 0, v[0:1]
	v_add_u32_e32 v133, 0xa000, v206
	v_lshl_add_u64 v[4:5], v[2:3], 0, s[6:7]
	s_mov_b32 m0, s2
	v_readfirstlane_b32 s2, v133
	global_load_lds_dwordx4 v[4:5], off
	v_lshl_add_u64 v[2:3], v[2:3], 0, s[8:9]
	s_mov_b32 m0, s2
	v_mov_b32_e32 v0, v203
	v_add_u32_e32 v134, s75, v202
	global_load_lds_dwordx4 v[2:3], off
	s_mov_b64 s[14:15], 0xb0080
	v_lshl_add_u64 v[2:3], s[0:1], 0, v[0:1]
	v_readfirstlane_b32 s2, v134
	v_add_u32_e32 v135, 0x2000, v134
	v_lshl_add_u64 v[4:5], v[2:3], 0, s[14:15]
	s_mov_b32 m0, s2
	s_mov_b64 s[16:17], 0x108080
	v_readfirstlane_b32 s2, v135
	global_load_lds_dwordx4 v[4:5], off
	v_lshl_add_u64 v[2:3], v[2:3], 0, s[16:17]
	s_mov_b32 m0, s2
	v_readlane_b32 s41, v252, 21
	global_load_lds_dwordx4 v[2:3], off
	s_waitcnt vmcnt(6)
	v_readlane_b32 s42, v252, 22
	v_readlane_b32 s43, v252, 23
	s_mov_b32 s2, -2
	s_mov_b64 s[6:7], 0
	s_waitcnt vmcnt(0)
	s_waitcnt lgkmcnt(0)
	s_mov_b64 s[18:19], 0x58100
	s_mov_b64 s[30:31], 0xb0100
	s_mov_b64 s[40:41], 0x108100
	s_mov_b64 s[42:43], 0x58180
	v_readlane_b32 s44, v252, 24
	v_readlane_b32 s45, v252, 25
	v_readlane_b32 s46, v252, 26
	v_readlane_b32 s47, v252, 27
	v_readlane_b32 s48, v252, 28
	v_readlane_b32 s49, v252, 29
	v_readlane_b32 s50, v252, 30
	v_readlane_b32 s51, v252, 31
	v_readlane_b32 s52, v252, 32
	v_readlane_b32 s53, v252, 33
	s_barrier
	v_add_u32_e32 v218, s21, v212
	v_readfirstlane_b32 s25, v206
	s_add_u32 s25, s25, 0xc000
	v_readfirstlane_b32 s32, v206
	s_add_u32 s32, s32, 0xe000
	v_add_u32_e32 v219, s33, v212
	v_readfirstlane_b32 s44, v204
	v_readfirstlane_b32 s45, v205
	v_readfirstlane_b32 s46, v206
	v_readfirstlane_b32 s47, v207
	v_readfirstlane_b32 s48, v208
	v_readfirstlane_b32 s49, v209
	v_add_u32_e32 v220, s96, v212
	v_readfirstlane_b32 s50, v210
	v_readfirstlane_b32 s51, v211
	v_add_u32_e32 v221, s75, v212
	v_readfirstlane_b32 s52, v130
	v_readfirstlane_b32 s53, v131
	v_readfirstlane_b32 s54, v132
	v_readfirstlane_b32 s55, v133
	v_readfirstlane_b32 s60, v134
	v_readfirstlane_b32 s61, v135
	v_add_u32_e32 v136, 0xc000, v206
	v_add_u32_e32 v137, 0xe000, v206
	ds_read_b128 v[138:141], v218
	ds_read_b128 v[142:145], v218 offset:1024
	ds_read_b128 v[146:149], v218 offset:2048
	ds_read_b128 v[150:153], v218 offset:3072
	s_add_u32 s8, s4, s6
	s_addc_u32 s9, s5, s7
	ds_read_b128 v[154:157], v213
	ds_read_b128 v[158:161], v213 offset:1024
	ds_read_b128 v[162:165], v213 offset:2048
	ds_read_b128 v[166:169], v213 offset:3072
	ds_read_b128 v[170:173], v213 offset:4096
	ds_read_b128 v[174:177], v213 offset:5120
	ds_read_b128 v[178:181], v213 offset:6144
	ds_read_b128 v[182:185], v213 offset:7168
	s_mov_b32 m0, s25
	s_add_u32 s98, s8, s14
	s_addc_u32 s99, s9, s15
	global_load_lds_dwordx4 v203, s[98:99]
	s_mov_b32 m0, s32
	s_add_u32 s98, s8, s16
	s_addc_u32 s99, s9, s17
	global_load_lds_dwordx4 v203, s[98:99]
	s_waitcnt lgkmcnt(8)
	s_waitcnt vmcnt(10)
	s_barrier
	s_waitcnt lgkmcnt(0)
	s_waitcnt lgkmcnt(0)
	v_mfma_f32_16x16x32_bf16 v[126:129], v[138:141], v[154:157], 0
	v_mfma_f32_16x16x32_bf16 v[122:125], v[146:149], v[154:157], 0
	v_mfma_f32_16x16x32_bf16 v[118:121], v[138:141], v[162:165], 0
	v_mfma_f32_16x16x32_bf16 v[114:117], v[146:149], v[162:165], 0
	v_mfma_f32_16x16x32_bf16 v[110:113], v[138:141], v[170:173], 0
	v_mfma_f32_16x16x32_bf16 v[106:109], v[146:149], v[170:173], 0
	v_mfma_f32_16x16x32_bf16 v[102:105], v[138:141], v[178:181], 0
	v_mfma_f32_16x16x32_bf16 v[98:101], v[146:149], v[178:181], 0
	v_mfma_f32_16x16x32_bf16 v[126:129], v[142:145], v[158:161], v[126:129]
	v_mfma_f32_16x16x32_bf16 v[122:125], v[150:153], v[158:161], v[122:125]
	v_mfma_f32_16x16x32_bf16 v[118:121], v[142:145], v[166:169], v[118:121]
	v_mfma_f32_16x16x32_bf16 v[114:117], v[150:153], v[166:169], v[114:117]
	v_mfma_f32_16x16x32_bf16 v[110:113], v[142:145], v[174:177], v[110:113]
	v_mfma_f32_16x16x32_bf16 v[106:109], v[150:153], v[174:177], v[106:109]
	v_mfma_f32_16x16x32_bf16 v[102:105], v[142:145], v[182:185], v[102:105]
	v_mfma_f32_16x16x32_bf16 v[98:101], v[150:153], v[182:185], v[98:101]
	s_barrier
	s_add_u32 vcc_lo, s0, s6
	ds_read_b128 v[186:189], v219
	ds_read_b128 v[190:193], v219 offset:1024
	ds_read_b128 v[194:197], v219 offset:2048
	ds_read_b128 v[198:201], v219 offset:3072
	s_addc_u32 vcc_hi, s1, s7
	s_mov_b32 m0, s44
	s_add_u32 s98, vcc_lo, s34
	s_addc_u32 s99, vcc_hi, s35
	global_load_lds_dwordx4 v203, s[98:99]
	s_mov_b32 m0, s45
	s_add_u32 s98, vcc_lo, s18
	s_addc_u32 s99, vcc_hi, s19
	global_load_lds_dwordx4 v203, s[98:99]
	s_waitcnt vmcnt(10)
	s_barrier
; #define LDA(dst, b, h) for (int m = 0; m < 4; ++m) for (int k = 0; k < 2; ++k) \
;     dst[m][k] = *reinterpret_cast<const bf16x8*>((char*)SA(b, h) + a_thr + (m * 2 + k) * 1024)
; #define LDB(dst, b, h) for (int n = 0; n < 2; ++n) for (int k = 0; k < 2; ++k) \
;     dst[n][k] = *reinterpret_cast<const bf16x8*>((char*)SB(b, h) + b_thr + (n * 2 + k) * 1024)
; #define MMA(ai, bj, At, Btf) do { __builtin_amdgcn_s_setprio(1); \
;     for (int m = 0; m < 4; ++m) for (int n = 0; n < 2; ++n) for (int k = 0; k < 2; ++k) \
;       acc[ai][bj][m][n] = __builtin_amdgcn_mfma_f32_16x16x32_bf16(Btf[n][k], At[m][k], acc[ai][bj][m][n], 0, 0, 0); \
;     __builtin_amdgcn_s_setprio(0); } while (0)
; #define WAIT_V(n) asm volatile("s_waitcnt vmcnt(" #n ")" ::: "memory")
; #define WAIT_L(n) asm volatile("s_waitcnt lgkmcnt(" #n ")" ::: "memory")
; #define BAR __builtin_amdgcn_s_barrier()
; #define SCHED __builtin_amdgcn_sched_barrier(0)
; template <bool OVL, bool PANEL = false, class Epi>
; __device__ __forceinline__ void gemm_phase(const bf16_t* __restrict__ A, long lda, const bf16_t* __restrict__ Bt, long ldb, int nM, int nN, int K,
;                                            const Epi& epi, bf16_t* shm, int w0) {
;     ...
;       BAR; WAIT_L(0); MMA(0, 1, At, B1); BAR;
;       LDA(At, 0, 1); STAGE(SA(0, 0), A, lda, aoff, brow, t + 2);
;       BAR; WAIT_L(0); MMA(1, 0, At, B0); BAR; SCHED;
;       STAGE(SB(0, 1), Bt, ldb, boff, bcol + HALF, t + 2);
;       WAIT_V(6); BAR; MMA(1, 1, At, B1); BAR;
;       LDB(B0, 1, 0); SCHED; LDA(At, 1, 0); STAGE(SA(0, 1), A, lda, aoff, brow + HALF, t + 2);
;       WAIT_L(8); BAR; WAIT_L(0); MMA(0, 0, At, B0); BAR; SCHED;
	s_waitcnt lgkmcnt(0)
	s_waitcnt lgkmcnt(0)
	v_mfma_f32_16x16x32_bf16 v[94:97], v[186:189], v[154:157], 0
	v_mfma_f32_16x16x32_bf16 v[90:93], v[194:197], v[154:157], 0
	v_mfma_f32_16x16x32_bf16 v[86:89], v[186:189], v[162:165], 0
	v_mfma_f32_16x16x32_bf16 v[82:85], v[194:197], v[162:165], 0
	v_mfma_f32_16x16x32_bf16 v[78:81], v[186:189], v[170:173], 0
	v_mfma_f32_16x16x32_bf16 v[74:77], v[194:197], v[170:173], 0
	v_mfma_f32_16x16x32_bf16 v[70:73], v[186:189], v[178:181], 0
	v_mfma_f32_16x16x32_bf16 v[66:69], v[194:197], v[178:181], 0
	v_mfma_f32_16x16x32_bf16 v[94:97], v[190:193], v[158:161], v[94:97]
	v_mfma_f32_16x16x32_bf16 v[90:93], v[198:201], v[158:161], v[90:93]
	v_mfma_f32_16x16x32_bf16 v[86:89], v[190:193], v[166:169], v[86:89]
	v_mfma_f32_16x16x32_bf16 v[82:85], v[198:201], v[166:169], v[82:85]
	v_mfma_f32_16x16x32_bf16 v[78:81], v[190:193], v[174:177], v[78:81]
	v_mfma_f32_16x16x32_bf16 v[74:77], v[198:201], v[174:177], v[74:77]
	v_mfma_f32_16x16x32_bf16 v[70:73], v[190:193], v[182:185], v[70:73]
	v_mfma_f32_16x16x32_bf16 v[66:69], v[198:201], v[182:185], v[66:69]
	s_barrier
	ds_read_b128 v[154:157], v213 offset:16384
	ds_read_b128 v[158:161], v213 offset:17408
	ds_read_b128 v[162:165], v213 offset:18432
	ds_read_b128 v[166:169], v213 offset:19456
	ds_read_b128 v[170:173], v213 offset:20480
	ds_read_b128 v[174:177], v213 offset:21504
	ds_read_b128 v[178:181], v213 offset:22528
	ds_read_b128 v[182:185], v213 offset:23552
	s_mov_b32 m0, s46
	s_add_u32 s98, s8, s34
	s_addc_u32 s99, s9, s35
	global_load_lds_dwordx4 v203, s[98:99]
	s_mov_b32 m0, s47
	s_add_u32 s98, s8, s18
	s_addc_u32 s99, s9, s19
	global_load_lds_dwordx4 v203, s[98:99]
	s_barrier
	s_waitcnt lgkmcnt(0)
	s_waitcnt lgkmcnt(0)
	v_mfma_f32_16x16x32_bf16 v[62:65], v[138:141], v[154:157], 0
	v_mfma_f32_16x16x32_bf16 v[58:61], v[146:149], v[154:157], 0
	v_mfma_f32_16x16x32_bf16 v[54:57], v[138:141], v[162:165], 0
	v_mfma_f32_16x16x32_bf16 v[50:53], v[146:149], v[162:165], 0
	v_mfma_f32_16x16x32_bf16 v[46:49], v[138:141], v[170:173], 0
	v_mfma_f32_16x16x32_bf16 v[42:45], v[146:149], v[170:173], 0
	v_mfma_f32_16x16x32_bf16 v[38:41], v[138:141], v[178:181], 0
	v_mfma_f32_16x16x32_bf16 v[34:37], v[146:149], v[178:181], 0
	v_mfma_f32_16x16x32_bf16 v[62:65], v[142:145], v[158:161], v[62:65]
	v_mfma_f32_16x16x32_bf16 v[58:61], v[150:153], v[158:161], v[58:61]
	v_mfma_f32_16x16x32_bf16 v[54:57], v[142:145], v[166:169], v[54:57]
	v_mfma_f32_16x16x32_bf16 v[50:53], v[150:153], v[166:169], v[50:53]
	v_mfma_f32_16x16x32_bf16 v[46:49], v[142:145], v[174:177], v[46:49]
	v_mfma_f32_16x16x32_bf16 v[42:45], v[150:153], v[174:177], v[42:45]
	v_mfma_f32_16x16x32_bf16 v[38:41], v[142:145], v[182:185], v[38:41]
	v_mfma_f32_16x16x32_bf16 v[34:37], v[150:153], v[182:185], v[34:37]
	s_barrier
	s_mov_b32 m0, s48
	s_add_u32 s98, vcc_lo, s30
	s_addc_u32 s99, vcc_hi, s31
	global_load_lds_dwordx4 v203, s[98:99]
	s_mov_b32 m0, s49
	s_add_u32 s98, vcc_lo, s40
	s_addc_u32 s99, vcc_hi, s41
	global_load_lds_dwordx4 v203, s[98:99]
	s_waitcnt vmcnt(10)
	s_barrier
	v_mfma_f32_16x16x32_bf16 v[30:33], v[186:189], v[154:157], 0
	v_mfma_f32_16x16x32_bf16 v[26:29], v[194:197], v[154:157], 0
	v_mfma_f32_16x16x32_bf16 v[22:25], v[186:189], v[162:165], 0
	v_mfma_f32_16x16x32_bf16 v[18:21], v[194:197], v[162:165], 0
	v_mfma_f32_16x16x32_bf16 v[14:17], v[186:189], v[170:173], 0
	v_mfma_f32_16x16x32_bf16 v[10:13], v[194:197], v[170:173], 0
	v_mfma_f32_16x16x32_bf16 v[6:9], v[186:189], v[178:181], 0
	v_mfma_f32_16x16x32_bf16 v[2:5], v[194:197], v[178:181], 0
	v_mfma_f32_16x16x32_bf16 v[30:33], v[190:193], v[158:161], v[30:33]
	v_mfma_f32_16x16x32_bf16 v[26:29], v[198:201], v[158:161], v[26:29]
	v_mfma_f32_16x16x32_bf16 v[22:25], v[190:193], v[166:169], v[22:25]
	v_mfma_f32_16x16x32_bf16 v[18:21], v[198:201], v[166:169], v[18:21]
	v_mfma_f32_16x16x32_bf16 v[14:17], v[190:193], v[174:177], v[14:17]
	v_mfma_f32_16x16x32_bf16 v[10:13], v[198:201], v[174:177], v[10:13]
	v_mfma_f32_16x16x32_bf16 v[6:9], v[190:193], v[182:185], v[6:9]
	v_mfma_f32_16x16x32_bf16 v[2:5], v[198:201], v[182:185], v[2:5]
	s_barrier
	ds_read_b128 v[138:141], v220
	ds_read_b128 v[142:145], v220 offset:1024
	ds_read_b128 v[146:149], v220 offset:2048
	ds_read_b128 v[150:153], v220 offset:3072
	ds_read_b128 v[154:157], v213 offset:32768
	ds_read_b128 v[158:161], v213 offset:33792
	ds_read_b128 v[162:165], v213 offset:34816
	ds_read_b128 v[166:169], v213 offset:35840
	ds_read_b128 v[170:173], v213 offset:36864
	ds_read_b128 v[174:177], v213 offset:37888
	ds_read_b128 v[178:181], v213 offset:38912
	ds_read_b128 v[182:185], v213 offset:39936
	s_mov_b32 m0, s50
	s_add_u32 s98, s8, s30
	s_addc_u32 s99, s9, s31
	global_load_lds_dwordx4 v203, s[98:99]
	s_mov_b32 m0, s51
	s_add_u32 s98, s8, s40
	s_addc_u32 s99, s9, s41
	global_load_lds_dwordx4 v203, s[98:99]
	s_waitcnt lgkmcnt(8)
	s_waitcnt vmcnt(10)
	s_barrier
; #define LDA(dst, b, h) for (int m = 0; m < 4; ++m) for (int k = 0; k < 2; ++k) \
;     dst[m][k] = *reinterpret_cast<const bf16x8*>((char*)SA(b, h) + a_thr + (m * 2 + k) * 1024)
; #define LDB(dst, b, h) for (int n = 0; n < 2; ++n) for (int k = 0; k < 2; ++k) \
;     dst[n][k] = *reinterpret_cast<const bf16x8*>((char*)SB(b, h) + b_thr + (n * 2 + k) * 1024)
; #define MMA(ai, bj, At, Btf) do { __builtin_amdgcn_s_setprio(1); \
;     for (int m = 0; m < 4; ++m) for (int n = 0; n < 2; ++n) for (int k = 0; k < 2; ++k) \
;       acc[ai][bj][m][n] = __builtin_amdgcn_mfma_f32_16x16x32_bf16(Btf[n][k], At[m][k], acc[ai][bj][m][n], 0, 0, 0); \
;     __builtin_amdgcn_s_setprio(0); } while (0)
; #define WAIT_V(n) asm volatile("s_waitcnt vmcnt(" #n ")" ::: "memory")
; #define WAIT_L(n) asm volatile("s_waitcnt lgkmcnt(" #n ")" ::: "memory")
; #define BAR __builtin_amdgcn_s_barrier()
; #define SCHED __builtin_amdgcn_sched_barrier(0)
; template <bool OVL, bool PANEL = false, class Epi>
; __device__ __forceinline__ void gemm_phase(const bf16_t* __restrict__ A, long lda, const bf16_t* __restrict__ Bt, long ldb, int nM, int nN, int K,
;                                            const Epi& epi, bf16_t* shm, int w0) {
;     ...
;       WAIT_L(8); BAR; WAIT_L(0); MMA(0, 0, At, B0); BAR; SCHED;
;       LDB(B1, 1, 1); STAGE(SB(1, 0), Bt, ldb, boff, bcol, t + 3);
;       BAR; WAIT_L(0); MMA(0, 1, At, B1); BAR;
;       LDA(At, 1, 1); STAGE(SA(1, 0), A, lda, aoff, brow, t + 3);
;       BAR; WAIT_L(0); MMA(1, 0, At, B0); BAR; SCHED;
;       STAGE(SB(1, 1), Bt, ldb, boff, bcol + HALF, t + 3);
;       WAIT_V(6); BAR; MMA(1, 1, At, B1); BAR;
	s_waitcnt lgkmcnt(0)
	s_waitcnt lgkmcnt(0)
	v_mfma_f32_16x16x32_bf16 v[126:129], v[138:141], v[154:157], v[126:129]
	v_mfma_f32_16x16x32_bf16 v[122:125], v[146:149], v[154:157], v[122:125]
	v_mfma_f32_16x16x32_bf16 v[118:121], v[138:141], v[162:165], v[118:121]
	v_mfma_f32_16x16x32_bf16 v[114:117], v[146:149], v[162:165], v[114:117]
	v_mfma_f32_16x16x32_bf16 v[110:113], v[138:141], v[170:173], v[110:113]
	v_mfma_f32_16x16x32_bf16 v[106:109], v[146:149], v[170:173], v[106:109]
	v_mfma_f32_16x16x32_bf16 v[102:105], v[138:141], v[178:181], v[102:105]
	v_mfma_f32_16x16x32_bf16 v[98:101], v[146:149], v[178:181], v[98:101]
	v_mfma_f32_16x16x32_bf16 v[126:129], v[142:145], v[158:161], v[126:129]
	v_mfma_f32_16x16x32_bf16 v[122:125], v[150:153], v[158:161], v[122:125]
	v_mfma_f32_16x16x32_bf16 v[118:121], v[142:145], v[166:169], v[118:121]
	v_mfma_f32_16x16x32_bf16 v[114:117], v[150:153], v[166:169], v[114:117]
	v_mfma_f32_16x16x32_bf16 v[110:113], v[142:145], v[174:177], v[110:113]
	v_mfma_f32_16x16x32_bf16 v[106:109], v[150:153], v[174:177], v[106:109]
	v_mfma_f32_16x16x32_bf16 v[102:105], v[142:145], v[182:185], v[102:105]
	v_mfma_f32_16x16x32_bf16 v[98:101], v[150:153], v[182:185], v[98:101]
	s_barrier
	ds_read_b128 v[186:189], v221
	ds_read_b128 v[190:193], v221 offset:1024
	ds_read_b128 v[194:197], v221 offset:2048
	ds_read_b128 v[198:201], v221 offset:3072
	s_mov_b32 m0, s52
	s_add_u32 s98, vcc_lo, s94
	s_addc_u32 s99, vcc_hi, s95
	global_load_lds_dwordx4 v203, s[98:99]
	s_mov_b32 m0, s53
	s_add_u32 s98, vcc_lo, s42
	s_addc_u32 s99, vcc_hi, s43
	global_load_lds_dwordx4 v203, s[98:99]
	s_waitcnt vmcnt(10)
	s_barrier
	s_waitcnt lgkmcnt(0)
	s_waitcnt lgkmcnt(0)
	v_mfma_f32_16x16x32_bf16 v[94:97], v[186:189], v[154:157], v[94:97]
	v_mfma_f32_16x16x32_bf16 v[90:93], v[194:197], v[154:157], v[90:93]
	v_mfma_f32_16x16x32_bf16 v[86:89], v[186:189], v[162:165], v[86:89]
	v_mfma_f32_16x16x32_bf16 v[82:85], v[194:197], v[162:165], v[82:85]
	v_mfma_f32_16x16x32_bf16 v[78:81], v[186:189], v[170:173], v[78:81]
	v_mfma_f32_16x16x32_bf16 v[74:77], v[194:197], v[170:173], v[74:77]
	v_mfma_f32_16x16x32_bf16 v[70:73], v[186:189], v[178:181], v[70:73]
	v_mfma_f32_16x16x32_bf16 v[66:69], v[194:197], v[178:181], v[66:69]
	v_mfma_f32_16x16x32_bf16 v[94:97], v[190:193], v[158:161], v[94:97]
	v_mfma_f32_16x16x32_bf16 v[90:93], v[198:201], v[158:161], v[90:93]
	v_mfma_f32_16x16x32_bf16 v[86:89], v[190:193], v[166:169], v[86:89]
	v_mfma_f32_16x16x32_bf16 v[82:85], v[198:201], v[166:169], v[82:85]
	v_mfma_f32_16x16x32_bf16 v[78:81], v[190:193], v[174:177], v[78:81]
	v_mfma_f32_16x16x32_bf16 v[74:77], v[198:201], v[174:177], v[74:77]
	v_mfma_f32_16x16x32_bf16 v[70:73], v[190:193], v[182:185], v[70:73]
	v_mfma_f32_16x16x32_bf16 v[66:69], v[198:201], v[182:185], v[66:69]
	s_barrier
	ds_read_b128 v[154:157], v213 offset:49152
	ds_read_b128 v[158:161], v213 offset:50176
	ds_read_b128 v[162:165], v213 offset:51200
	ds_read_b128 v[166:169], v213 offset:52224
	ds_read_b128 v[170:173], v213 offset:53248
	ds_read_b128 v[174:177], v213 offset:54272
	ds_read_b128 v[178:181], v213 offset:55296
	ds_read_b128 v[182:185], v213 offset:56320
	s_mov_b32 m0, s54
	s_add_u32 s98, s8, s94
	s_addc_u32 s99, s9, s95
	global_load_lds_dwordx4 v203, s[98:99]
	s_mov_b32 m0, s55
	s_add_u32 s98, s8, s42
	s_addc_u32 s99, s9, s43
	global_load_lds_dwordx4 v203, s[98:99]
	s_barrier
	s_waitcnt lgkmcnt(0)
	s_waitcnt lgkmcnt(0)
	v_mfma_f32_16x16x32_bf16 v[62:65], v[138:141], v[154:157], v[62:65]
	v_mfma_f32_16x16x32_bf16 v[58:61], v[146:149], v[154:157], v[58:61]
	v_mfma_f32_16x16x32_bf16 v[54:57], v[138:141], v[162:165], v[54:57]
	v_mfma_f32_16x16x32_bf16 v[50:53], v[146:149], v[162:165], v[50:53]
	v_mfma_f32_16x16x32_bf16 v[46:49], v[138:141], v[170:173], v[46:49]
	v_mfma_f32_16x16x32_bf16 v[42:45], v[146:149], v[170:173], v[42:45]
	v_mfma_f32_16x16x32_bf16 v[38:41], v[138:141], v[178:181], v[38:41]
	v_mfma_f32_16x16x32_bf16 v[34:37], v[146:149], v[178:181], v[34:37]
	v_mfma_f32_16x16x32_bf16 v[62:65], v[142:145], v[158:161], v[62:65]
	v_mfma_f32_16x16x32_bf16 v[58:61], v[150:153], v[158:161], v[58:61]
	v_mfma_f32_16x16x32_bf16 v[54:57], v[142:145], v[166:169], v[54:57]
	v_mfma_f32_16x16x32_bf16 v[50:53], v[150:153], v[166:169], v[50:53]
	v_mfma_f32_16x16x32_bf16 v[46:49], v[142:145], v[174:177], v[46:49]
	v_mfma_f32_16x16x32_bf16 v[42:45], v[150:153], v[174:177], v[42:45]
	v_mfma_f32_16x16x32_bf16 v[38:41], v[142:145], v[182:185], v[38:41]
	v_mfma_f32_16x16x32_bf16 v[34:37], v[150:153], v[182:185], v[34:37]
	s_barrier
	s_mov_b64 s[8:9], 0xb0180
	s_mov_b64 s[8:9], 0x108180
	s_mov_b32 m0, s60
	s_add_u32 s98, vcc_lo, 0xb0180
	s_addc_u32 s99, vcc_hi, 0
	global_load_lds_dwordx4 v203, s[98:99]
	s_mov_b32 m0, s61
	s_add_u32 s98, vcc_lo, 0x108180
	s_addc_u32 s99, vcc_hi, 0
	global_load_lds_dwordx4 v203, s[98:99]
	s_add_i32 s2, s2, 2
	s_add_u32 s6, s6, 0x100
	s_addc_u32 s7, s7, 0
	s_cmp_gt_u32 s2, 39
	s_waitcnt vmcnt(10)
	s_barrier
	v_mfma_f32_16x16x32_bf16 v[30:33], v[186:189], v[154:157], v[30:33]
	v_mfma_f32_16x16x32_bf16 v[26:29], v[194:197], v[154:157], v[26:29]
	v_mfma_f32_16x16x32_bf16 v[22:25], v[186:189], v[162:165], v[22:25]
	v_mfma_f32_16x16x32_bf16 v[18:21], v[194:197], v[162:165], v[18:21]
	v_mfma_f32_16x16x32_bf16 v[14:17], v[186:189], v[170:173], v[14:17]
	v_mfma_f32_16x16x32_bf16 v[10:13], v[194:197], v[170:173], v[10:13]
	v_mfma_f32_16x16x32_bf16 v[6:9], v[186:189], v[178:181], v[6:9]
	v_mfma_f32_16x16x32_bf16 v[2:5], v[194:197], v[178:181], v[2:5]
	v_mfma_f32_16x16x32_bf16 v[30:33], v[190:193], v[158:161], v[30:33]
	v_mfma_f32_16x16x32_bf16 v[26:29], v[198:201], v[158:161], v[26:29]
	v_mfma_f32_16x16x32_bf16 v[22:25], v[190:193], v[166:169], v[22:25]
	v_mfma_f32_16x16x32_bf16 v[18:21], v[198:201], v[166:169], v[18:21]
	v_mfma_f32_16x16x32_bf16 v[14:17], v[190:193], v[174:177], v[14:17]
	v_mfma_f32_16x16x32_bf16 v[10:13], v[198:201], v[174:177], v[10:13]
	v_mfma_f32_16x16x32_bf16 v[6:9], v[190:193], v[182:185], v[6:9]
	v_mfma_f32_16x16x32_bf16 v[2:5], v[198:201], v[182:185], v[2:5]
	s_barrier

; #define LDA(dst, b, h) for (int m = 0; m < 4; ++m) for (int k = 0; k < 2; ++k) \
;     dst[m][k] = *reinterpret_cast<const bf16x8*>((char*)SA(b, h) + a_thr + (m * 2 + k) * 1024)
; #define LDB(dst, b, h) for (int n = 0; n < 2; ++n) for (int k = 0; k < 2; ++k) \
;     dst[n][k] = *reinterpret_cast<const bf16x8*>((char*)SB(b, h) + b_thr + (n * 2 + k) * 1024)
; #define MMA(ai, bj, At, Btf) do { __builtin_amdgcn_s_setprio(1); \
;     for (int m = 0; m < 4; ++m) for (int n = 0; n < 2; ++n) for (int k = 0; k < 2; ++k) \
;       acc[ai][bj][m][n] = __builtin_amdgcn_mfma_f32_16x16x32_bf16(Btf[n][k], At[m][k], acc[ai][bj][m][n], 0, 0, 0); \
;     __builtin_amdgcn_s_setprio(0); } while (0)
; #define WAIT_V(n) asm volatile("s_waitcnt vmcnt(" #n ")" ::: "memory")
; #define WAIT_L(n) asm volatile("s_waitcnt lgkmcnt(" #n ")" ::: "memory")
; #define BAR __builtin_amdgcn_s_barrier()
; #define SCHED __builtin_amdgcn_sched_barrier(0)
; template <bool OVL, bool PANEL = false, class Epi>
; __device__ __forceinline__ void gemm_phase(const bf16_t* __restrict__ A, long lda, const bf16_t* __restrict__ Bt, long ldb, int nM, int nN, int K,
;                                            const Epi& epi, bf16_t* shm, int w0) {
;     ...
;   for (int it = 0; have; ++it) {
;     const int brow = pm * BM, bcol = pn * BM;
;     f32x4 acc[2][2][4][2];
; #pragma unroll
;     for (int a0 = 0; a0 < 2; ++a0)
; #pragma unroll
;       for (int a1 = 0; a1 < 2; ++a1)
; #pragma unroll
;         for (int a2 = 0; a2 < 4; ++a2)
; #pragma unroll
;           for (int a3 = 0; a3 < 2; ++a3) acc[a0][a1][a2][a3] = (f32x4){0.f, 0.f, 0.f, 0.f};
;     bf16x8 At[4][2], B0[2][2], B1[2][2];
;     if (wr == 1) BAR;
;     WAIT_V(4); BAR;
;     STAGE(SB(1, 0), Bt, ldb, boff, bcol, 1); STAGE(SA(1, 0), A, lda, aoff, brow, 1); STAGE(SB(1, 1), Bt, ldb, boff, bcol + HALF, 1);
;     WAIT_V(6); BAR;
;     for (int t = 0; t < nt - 2; t += 2) {
;       LDB(B0, 0, 0); SCHED; LDA(At, 0, 0); STAGE(SA(1, 1), A, lda, aoff, brow + HALF, t + 1);
;       WAIT_L(8); BAR; WAIT_L(0); MMA(0, 0, At, B0); BAR; SCHED;
;       LDB(B1, 0, 1); STAGE(SB(0, 0), Bt, ldb, boff, bcol, t + 2);
.LBB0_385:
	s_or_b64 exec, exec, s[6:7]
	s_lshl_b32 s6, s24, 8
	s_ashr_i32 s7, s6, 31
	s_lshl_b32 s2, s25, 8
	s_lshl_b64 s[8:9], s[6:7], 11
	v_readlane_b32 s80, v251, 49
	v_readlane_b32 s81, v251, 50
	s_add_u32 s8, s80, s8
	s_addc_u32 s9, s81, s9
	v_mov_b32_e32 v0, v131
	v_add_u32_e32 v142, s96, v130
	s_waitcnt vmcnt(4)
	s_barrier
	s_mov_b64 s[30:31], 0x80
	v_lshl_add_u64 v[2:3], s[8:9], 0, v[0:1]
	v_readfirstlane_b32 s10, v142
	v_add_u32_e32 v143, 0x2000, v142
	v_lshl_add_u64 v[4:5], v[2:3], 0, s[30:31]
	s_mov_b32 m0, s10
	v_readfirstlane_b32 s10, v143
	v_readlane_b32 s44, v252, 20
	global_load_lds_dwordx4 v[4:5], off
	s_mov_b32 m0, s10
	s_lshl_b64 s[10:11], s[2:3], 11
	v_readlane_b32 s50, v252, 26
	v_readlane_b32 s51, v252, 27
	s_add_u32 s10, s50, s10
	s_mov_b64 s[42:43], 0x20080
	s_addc_u32 s11, s51, s11
	s_or_b32 s28, s6, 0x80
	v_lshl_add_u64 v[2:3], v[2:3], 0, s[42:43]
	v_mov_b32_e32 v0, v131
	v_add_u32_e32 v144, 0x8000, v134
	s_ashr_i32 s29, s28, 31
	global_load_lds_dwordx4 v[2:3], off
	v_readfirstlane_b32 s18, v144
	v_lshl_add_u64 v[2:3], s[10:11], 0, v[0:1]
	v_add_u32_e32 v145, 0xa000, v134
	s_lshl_b64 s[28:29], s[28:29], 11
	v_lshl_add_u64 v[4:5], v[2:3], 0, s[30:31]
	s_mov_b32 m0, s18
	v_readfirstlane_b32 s18, v145
	s_add_u32 s28, s80, s28
	global_load_lds_dwordx4 v[4:5], off
	v_lshl_add_u64 v[2:3], v[2:3], 0, s[42:43]
	s_mov_b32 m0, s18
	s_addc_u32 s29, s81, s29
	v_mov_b32_e32 v0, v131
	v_add_u32_e32 v146, s75, v130
	global_load_lds_dwordx4 v[2:3], off
	v_readfirstlane_b32 s18, v146
	v_lshl_add_u64 v[2:3], s[28:29], 0, v[0:1]
	v_add_u32_e32 v147, 0x2000, v146
	v_lshl_add_u64 v[4:5], v[2:3], 0, s[30:31]
	s_mov_b32 m0, s18
	v_readfirstlane_b32 s18, v147
	global_load_lds_dwordx4 v[4:5], off
	v_lshl_add_u64 v[2:3], v[2:3], 0, s[42:43]
	s_mov_b32 m0, s18
	v_readlane_b32 s45, v252, 21
	global_load_lds_dwordx4 v[2:3], off
	s_waitcnt vmcnt(6)
	s_mov_b32 s18, -2
	s_mov_b64 vcc, 0
	s_waitcnt vmcnt(0)
	s_waitcnt lgkmcnt(0)
	s_mov_b64 s[28:29], 0x40080
	s_mov_b64 s[30:31], 0x40180
	s_mov_b64 s[44:45], 0x60180
	v_readlane_b32 s82, v251, 51
	v_readlane_b32 s83, v251, 52
	v_readlane_b32 s84, v251, 53
	v_readlane_b32 s85, v251, 54
	v_readlane_b32 s86, v251, 55
	v_readlane_b32 s87, v251, 56
	v_readlane_b32 s46, v252, 22
	v_readlane_b32 s47, v252, 23
	v_readlane_b32 s48, v252, 24
	v_readlane_b32 s49, v252, 25
	v_readlane_b32 s52, v252, 28
	v_readlane_b32 s53, v252, 29
	v_readlane_b32 s54, v252, 30
	v_readlane_b32 s55, v252, 31
	v_readlane_b32 s56, v252, 32
	v_readlane_b32 s57, v252, 33
	v_readlane_b32 s58, v252, 34
	v_readlane_b32 s59, v252, 35
	s_barrier
	v_add_u32_e32 v218, s21, v140
	v_readfirstlane_b32 s16, v134
	s_add_u32 s16, s16, 0xc000
	v_readfirstlane_b32 s32, v134
	s_add_u32 s32, s32, 0xe000
	v_add_u32_e32 v219, s33, v140
	v_readfirstlane_b32 s46, v132
	v_readfirstlane_b32 s47, v133
	v_readfirstlane_b32 s48, v134
	v_readfirstlane_b32 s49, v135
	v_readfirstlane_b32 s50, v136
	v_readfirstlane_b32 s51, v137
	v_add_u32_e32 v220, s96, v140
	v_readfirstlane_b32 s52, v138
	v_readfirstlane_b32 s53, v139
	v_add_u32_e32 v221, s75, v140
	v_readfirstlane_b32 s54, v142
	v_readfirstlane_b32 s55, v143
	v_readfirstlane_b32 s56, v144
	v_readfirstlane_b32 s57, v145
	v_readfirstlane_b32 s58, v146
	v_readfirstlane_b32 s59, v147
	v_add_u32_e32 v148, 0xc000, v134
	v_add_u32_e32 v149, 0xe000, v134
	ds_read_b128 v[150:153], v218
	ds_read_b128 v[154:157], v218 offset:1024
	ds_read_b128 v[158:161], v218 offset:2048
	ds_read_b128 v[162:165], v218 offset:3072
	s_add_u32 s42, s10, vcc_lo
	s_addc_u32 s43, s11, vcc_hi
	ds_read_b128 v[166:169], v141
	ds_read_b128 v[170:173], v141 offset:1024
	ds_read_b128 v[174:177], v141 offset:2048
	ds_read_b128 v[178:181], v141 offset:3072
	ds_read_b128 v[182:185], v141 offset:4096
	ds_read_b128 v[186:189], v141 offset:5120
	ds_read_b128 v[190:193], v141 offset:6144
	ds_read_b128 v[194:197], v141 offset:7168
	s_mov_b32 m0, s16
	s_add_u32 s98, s42, s28
	s_addc_u32 s99, s43, s29
	global_load_lds_dwordx4 v131, s[98:99]
	s_mov_b32 m0, s32
	s_add_u32 s98, s42, s36
	s_addc_u32 s99, s43, s37
	global_load_lds_dwordx4 v131, s[98:99]
	s_waitcnt lgkmcnt(8)
	s_waitcnt vmcnt(10)
	s_barrier
	s_waitcnt lgkmcnt(0)
	s_waitcnt lgkmcnt(0)
	v_mfma_f32_16x16x32_bf16 v[126:129], v[150:153], v[166:169], 0
	v_mfma_f32_16x16x32_bf16 v[122:125], v[158:161], v[166:169], 0
	v_mfma_f32_16x16x32_bf16 v[118:121], v[150:153], v[174:177], 0
	v_mfma_f32_16x16x32_bf16 v[114:117], v[158:161], v[174:177], 0
	v_mfma_f32_16x16x32_bf16 v[110:113], v[150:153], v[182:185], 0
	v_mfma_f32_16x16x32_bf16 v[106:109], v[158:161], v[182:185], 0
	v_mfma_f32_16x16x32_bf16 v[102:105], v[150:153], v[190:193], 0
	v_mfma_f32_16x16x32_bf16 v[98:101], v[158:161], v[190:193], 0
	v_mfma_f32_16x16x32_bf16 v[126:129], v[154:157], v[170:173], v[126:129]
	v_mfma_f32_16x16x32_bf16 v[122:125], v[162:165], v[170:173], v[122:125]
	v_mfma_f32_16x16x32_bf16 v[118:121], v[154:157], v[178:181], v[118:121]
	v_mfma_f32_16x16x32_bf16 v[114:117], v[162:165], v[178:181], v[114:117]
	v_mfma_f32_16x16x32_bf16 v[110:113], v[154:157], v[186:189], v[110:113]
	v_mfma_f32_16x16x32_bf16 v[106:109], v[162:165], v[186:189], v[106:109]
	v_mfma_f32_16x16x32_bf16 v[102:105], v[154:157], v[194:197], v[102:105]
	v_mfma_f32_16x16x32_bf16 v[98:101], v[162:165], v[194:197], v[98:101]
	s_barrier
	s_add_u32 s66, s8, vcc_lo
	ds_read_b128 v[198:201], v219
	ds_read_b128 v[202:205], v219 offset:1024
	ds_read_b128 v[206:209], v219 offset:2048
	ds_read_b128 v[210:213], v219 offset:3072
	s_addc_u32 s67, s9, vcc_hi
	s_mov_b32 m0, s46
	s_add_u32 s98, s66, s34
	s_addc_u32 s99, s67, s35
	global_load_lds_dwordx4 v131, s[98:99]
	s_mov_b32 m0, s47
	s_add_u32 s98, s66, s64
	s_addc_u32 s99, s67, s65
	global_load_lds_dwordx4 v131, s[98:99]
	s_waitcnt vmcnt(10)
	s_barrier
; #define LDA(dst, b, h) for (int m = 0; m < 4; ++m) for (int k = 0; k < 2; ++k) \
;     dst[m][k] = *reinterpret_cast<const bf16x8*>((char*)SA(b, h) + a_thr + (m * 2 + k) * 1024)
; #define LDB(dst, b, h) for (int n = 0; n < 2; ++n) for (int k = 0; k < 2; ++k) \
;     dst[n][k] = *reinterpret_cast<const bf16x8*>((char*)SB(b, h) + b_thr + (n * 2 + k) * 1024)
; #define MMA(ai, bj, At, Btf) do { __builtin_amdgcn_s_setprio(1); \
;     for (int m = 0; m < 4; ++m) for (int n = 0; n < 2; ++n) for (int k = 0; k < 2; ++k) \
;       acc[ai][bj][m][n] = __builtin_amdgcn_mfma_f32_16x16x32_bf16(Btf[n][k], At[m][k], acc[ai][bj][m][n], 0, 0, 0); \
;     __builtin_amdgcn_s_setprio(0); } while (0)
; #define WAIT_V(n) asm volatile("s_waitcnt vmcnt(" #n ")" ::: "memory")
; #define WAIT_L(n) asm volatile("s_waitcnt lgkmcnt(" #n ")" ::: "memory")
; #define BAR __builtin_amdgcn_s_barrier()
; #define SCHED __builtin_amdgcn_sched_barrier(0)
; template <bool OVL, bool PANEL = false, class Epi>
; __device__ __forceinline__ void gemm_phase(const bf16_t* __restrict__ A, long lda, const bf16_t* __restrict__ Bt, long ldb, int nM, int nN, int K,
;                                            const Epi& epi, bf16_t* shm, int w0) {
;     ...
;       BAR; WAIT_L(0); MMA(0, 1, At, B1); BAR;
;       LDA(At, 0, 1); STAGE(SA(0, 0), A, lda, aoff, brow, t + 2);
;       BAR; WAIT_L(0); MMA(1, 0, At, B0); BAR; SCHED;
;       STAGE(SB(0, 1), Bt, ldb, boff, bcol + HALF, t + 2);
;       WAIT_V(6); BAR; MMA(1, 1, At, B1); BAR;
;       LDB(B0, 1, 0); SCHED; LDA(At, 1, 0); STAGE(SA(0, 1), A, lda, aoff, brow + HALF, t + 2);
;       WAIT_L(8); BAR; WAIT_L(0); MMA(0, 0, At, B0); BAR; SCHED;
	s_waitcnt lgkmcnt(0)
	s_waitcnt lgkmcnt(0)
	v_mfma_f32_16x16x32_bf16 v[94:97], v[198:201], v[166:169], 0
	v_mfma_f32_16x16x32_bf16 v[90:93], v[206:209], v[166:169], 0
	v_mfma_f32_16x16x32_bf16 v[86:89], v[198:201], v[174:177], 0
	v_mfma_f32_16x16x32_bf16 v[82:85], v[206:209], v[174:177], 0
	v_mfma_f32_16x16x32_bf16 v[78:81], v[198:201], v[182:185], 0
	v_mfma_f32_16x16x32_bf16 v[74:77], v[206:209], v[182:185], 0
	v_mfma_f32_16x16x32_bf16 v[70:73], v[198:201], v[190:193], 0
	v_mfma_f32_16x16x32_bf16 v[66:69], v[206:209], v[190:193], 0
	v_mfma_f32_16x16x32_bf16 v[94:97], v[202:205], v[170:173], v[94:97]
	v_mfma_f32_16x16x32_bf16 v[90:93], v[210:213], v[170:173], v[90:93]
	v_mfma_f32_16x16x32_bf16 v[86:89], v[202:205], v[178:181], v[86:89]
	v_mfma_f32_16x16x32_bf16 v[82:85], v[210:213], v[178:181], v[82:85]
	v_mfma_f32_16x16x32_bf16 v[78:81], v[202:205], v[186:189], v[78:81]
	v_mfma_f32_16x16x32_bf16 v[74:77], v[210:213], v[186:189], v[74:77]
	v_mfma_f32_16x16x32_bf16 v[70:73], v[202:205], v[194:197], v[70:73]
	v_mfma_f32_16x16x32_bf16 v[66:69], v[210:213], v[194:197], v[66:69]
	s_barrier
	ds_read_b128 v[166:169], v141 offset:16384
	ds_read_b128 v[170:173], v141 offset:17408
	ds_read_b128 v[174:177], v141 offset:18432
	ds_read_b128 v[178:181], v141 offset:19456
	ds_read_b128 v[182:185], v141 offset:20480
	ds_read_b128 v[186:189], v141 offset:21504
	ds_read_b128 v[190:193], v141 offset:22528
	ds_read_b128 v[194:197], v141 offset:23552
	s_mov_b32 m0, s48
	s_add_u32 s98, s42, s34
	s_addc_u32 s99, s43, s35
	global_load_lds_dwordx4 v131, s[98:99]
	s_mov_b32 m0, s49
	s_add_u32 s98, s42, s64
	s_addc_u32 s99, s43, s65
	global_load_lds_dwordx4 v131, s[98:99]
	s_barrier
	s_waitcnt lgkmcnt(0)
	s_waitcnt lgkmcnt(0)
	v_mfma_f32_16x16x32_bf16 v[62:65], v[150:153], v[166:169], 0
	v_mfma_f32_16x16x32_bf16 v[58:61], v[158:161], v[166:169], 0
	v_mfma_f32_16x16x32_bf16 v[54:57], v[150:153], v[174:177], 0
	v_mfma_f32_16x16x32_bf16 v[50:53], v[158:161], v[174:177], 0
	v_mfma_f32_16x16x32_bf16 v[46:49], v[150:153], v[182:185], 0
	v_mfma_f32_16x16x32_bf16 v[42:45], v[158:161], v[182:185], 0
	v_mfma_f32_16x16x32_bf16 v[38:41], v[150:153], v[190:193], 0
	v_mfma_f32_16x16x32_bf16 v[34:37], v[158:161], v[190:193], 0
	v_mfma_f32_16x16x32_bf16 v[62:65], v[154:157], v[170:173], v[62:65]
	v_mfma_f32_16x16x32_bf16 v[58:61], v[162:165], v[170:173], v[58:61]
	v_mfma_f32_16x16x32_bf16 v[54:57], v[154:157], v[178:181], v[54:57]
	v_mfma_f32_16x16x32_bf16 v[50:53], v[162:165], v[178:181], v[50:53]
	v_mfma_f32_16x16x32_bf16 v[46:49], v[154:157], v[186:189], v[46:49]
	v_mfma_f32_16x16x32_bf16 v[42:45], v[162:165], v[186:189], v[42:45]
	v_mfma_f32_16x16x32_bf16 v[38:41], v[154:157], v[194:197], v[38:41]
	v_mfma_f32_16x16x32_bf16 v[34:37], v[162:165], v[194:197], v[34:37]
	s_barrier
	s_mov_b32 m0, s50
	s_add_u32 s98, s66, s68
	s_addc_u32 s99, s67, s69
	global_load_lds_dwordx4 v131, s[98:99]
	s_mov_b32 m0, s51
	s_add_u32 s98, s66, s70
	s_addc_u32 s99, s67, s71
	global_load_lds_dwordx4 v131, s[98:99]
	s_waitcnt vmcnt(10)
	s_barrier
	v_mfma_f32_16x16x32_bf16 v[30:33], v[198:201], v[166:169], 0
	v_mfma_f32_16x16x32_bf16 v[26:29], v[206:209], v[166:169], 0
	v_mfma_f32_16x16x32_bf16 v[22:25], v[198:201], v[174:177], 0
	v_mfma_f32_16x16x32_bf16 v[18:21], v[206:209], v[174:177], 0
	v_mfma_f32_16x16x32_bf16 v[14:17], v[198:201], v[182:185], 0
	v_mfma_f32_16x16x32_bf16 v[10:13], v[206:209], v[182:185], 0
	v_mfma_f32_16x16x32_bf16 v[6:9], v[198:201], v[190:193], 0
	v_mfma_f32_16x16x32_bf16 v[2:5], v[206:209], v[190:193], 0
	v_mfma_f32_16x16x32_bf16 v[30:33], v[202:205], v[170:173], v[30:33]
	v_mfma_f32_16x16x32_bf16 v[26:29], v[210:213], v[170:173], v[26:29]
	v_mfma_f32_16x16x32_bf16 v[22:25], v[202:205], v[178:181], v[22:25]
	v_mfma_f32_16x16x32_bf16 v[18:21], v[210:213], v[178:181], v[18:21]
	v_mfma_f32_16x16x32_bf16 v[14:17], v[202:205], v[186:189], v[14:17]
	v_mfma_f32_16x16x32_bf16 v[10:13], v[210:213], v[186:189], v[10:13]
	v_mfma_f32_16x16x32_bf16 v[6:9], v[202:205], v[194:197], v[6:9]
	v_mfma_f32_16x16x32_bf16 v[2:5], v[210:213], v[194:197], v[2:5]
	s_barrier
	ds_read_b128 v[150:153], v220
	ds_read_b128 v[154:157], v220 offset:1024
	ds_read_b128 v[158:161], v220 offset:2048
	ds_read_b128 v[162:165], v220 offset:3072
	ds_read_b128 v[166:169], v141 offset:32768
	ds_read_b128 v[170:173], v141 offset:33792
	ds_read_b128 v[174:177], v141 offset:34816
	ds_read_b128 v[178:181], v141 offset:35840
	ds_read_b128 v[182:185], v141 offset:36864
	ds_read_b128 v[186:189], v141 offset:37888
	ds_read_b128 v[190:193], v141 offset:38912
	ds_read_b128 v[194:197], v141 offset:39936
	s_mov_b32 m0, s52
	s_add_u32 s98, s42, s68
	s_addc_u32 s99, s43, s69
	global_load_lds_dwordx4 v131, s[98:99]
	s_mov_b32 m0, s53
	s_add_u32 s98, s42, s70
	s_addc_u32 s99, s43, s71
	global_load_lds_dwordx4 v131, s[98:99]
	s_waitcnt lgkmcnt(8)
	s_waitcnt vmcnt(10)
	s_barrier
; #define LDA(dst, b, h) for (int m = 0; m < 4; ++m) for (int k = 0; k < 2; ++k) \
;     dst[m][k] = *reinterpret_cast<const bf16x8*>((char*)SA(b, h) + a_thr + (m * 2 + k) * 1024)
; #define LDB(dst, b, h) for (int n = 0; n < 2; ++n) for (int k = 0; k < 2; ++k) \
;     dst[n][k] = *reinterpret_cast<const bf16x8*>((char*)SB(b, h) + b_thr + (n * 2 + k) * 1024)
; #define MMA(ai, bj, At, Btf) do { __builtin_amdgcn_s_setprio(1); \
;     for (int m = 0; m < 4; ++m) for (int n = 0; n < 2; ++n) for (int k = 0; k < 2; ++k) \
;       acc[ai][bj][m][n] = __builtin_amdgcn_mfma_f32_16x16x32_bf16(Btf[n][k], At[m][k], acc[ai][bj][m][n], 0, 0, 0); \
;     __builtin_amdgcn_s_setprio(0); } while (0)
; #define WAIT_V(n) asm volatile("s_waitcnt vmcnt(" #n ")" ::: "memory")
; #define WAIT_L(n) asm volatile("s_waitcnt lgkmcnt(" #n ")" ::: "memory")
; #define BAR __builtin_amdgcn_s_barrier()
; #define SCHED __builtin_amdgcn_sched_barrier(0)
; template <bool OVL, bool PANEL = false, class Epi>
; __device__ __forceinline__ void gemm_phase(const bf16_t* __restrict__ A, long lda, const bf16_t* __restrict__ Bt, long ldb, int nM, int nN, int K,
;                                            const Epi& epi, bf16_t* shm, int w0) {
;     ...
;       WAIT_L(8); BAR; WAIT_L(0); MMA(0, 0, At, B0); BAR; SCHED;
;       LDB(B1, 1, 1); STAGE(SB(1, 0), Bt, ldb, boff, bcol, t + 3);
;       BAR; WAIT_L(0); MMA(0, 1, At, B1); BAR;
;       LDA(At, 1, 1); STAGE(SA(1, 0), A, lda, aoff, brow, t + 3);
;       BAR; WAIT_L(0); MMA(1, 0, At, B0); BAR; SCHED;
;       STAGE(SB(1, 1), Bt, ldb, boff, bcol + HALF, t + 3);
;       WAIT_V(6); BAR; MMA(1, 1, At, B1); BAR;
	s_waitcnt lgkmcnt(0)
	s_waitcnt lgkmcnt(0)
	v_mfma_f32_16x16x32_bf16 v[126:129], v[150:153], v[166:169], v[126:129]
	v_mfma_f32_16x16x32_bf16 v[122:125], v[158:161], v[166:169], v[122:125]
	v_mfma_f32_16x16x32_bf16 v[118:121], v[150:153], v[174:177], v[118:121]
	v_mfma_f32_16x16x32_bf16 v[114:117], v[158:161], v[174:177], v[114:117]
	v_mfma_f32_16x16x32_bf16 v[110:113], v[150:153], v[182:185], v[110:113]
	v_mfma_f32_16x16x32_bf16 v[106:109], v[158:161], v[182:185], v[106:109]
	v_mfma_f32_16x16x32_bf16 v[102:105], v[150:153], v[190:193], v[102:105]
	v_mfma_f32_16x16x32_bf16 v[98:101], v[158:161], v[190:193], v[98:101]
	v_mfma_f32_16x16x32_bf16 v[126:129], v[154:157], v[170:173], v[126:129]
	v_mfma_f32_16x16x32_bf16 v[122:125], v[162:165], v[170:173], v[122:125]
	v_mfma_f32_16x16x32_bf16 v[118:121], v[154:157], v[178:181], v[118:121]
	v_mfma_f32_16x16x32_bf16 v[114:117], v[162:165], v[178:181], v[114:117]
	v_mfma_f32_16x16x32_bf16 v[110:113], v[154:157], v[186:189], v[110:113]
	v_mfma_f32_16x16x32_bf16 v[106:109], v[162:165], v[186:189], v[106:109]
	v_mfma_f32_16x16x32_bf16 v[102:105], v[154:157], v[194:197], v[102:105]
	v_mfma_f32_16x16x32_bf16 v[98:101], v[162:165], v[194:197], v[98:101]
	s_barrier
	ds_read_b128 v[198:201], v221
	ds_read_b128 v[202:205], v221 offset:1024
	ds_read_b128 v[206:209], v221 offset:2048
	ds_read_b128 v[210:213], v221 offset:3072
	s_mov_b32 m0, s54
	s_add_u32 s98, s66, s94
	s_addc_u32 s99, s67, s95
	global_load_lds_dwordx4 v131, s[98:99]
	s_mov_b32 m0, s55
	s_add_u32 s98, s66, s72
	s_addc_u32 s99, s67, s73
	global_load_lds_dwordx4 v131, s[98:99]
	s_waitcnt vmcnt(10)
	s_barrier
	s_waitcnt lgkmcnt(0)
	s_waitcnt lgkmcnt(0)
	v_mfma_f32_16x16x32_bf16 v[94:97], v[198:201], v[166:169], v[94:97]
	v_mfma_f32_16x16x32_bf16 v[90:93], v[206:209], v[166:169], v[90:93]
	v_mfma_f32_16x16x32_bf16 v[86:89], v[198:201], v[174:177], v[86:89]
	v_mfma_f32_16x16x32_bf16 v[82:85], v[206:209], v[174:177], v[82:85]
	v_mfma_f32_16x16x32_bf16 v[78:81], v[198:201], v[182:185], v[78:81]
	v_mfma_f32_16x16x32_bf16 v[74:77], v[206:209], v[182:185], v[74:77]
	v_mfma_f32_16x16x32_bf16 v[70:73], v[198:201], v[190:193], v[70:73]
	v_mfma_f32_16x16x32_bf16 v[66:69], v[206:209], v[190:193], v[66:69]
	v_mfma_f32_16x16x32_bf16 v[94:97], v[202:205], v[170:173], v[94:97]
	v_mfma_f32_16x16x32_bf16 v[90:93], v[210:213], v[170:173], v[90:93]
	v_mfma_f32_16x16x32_bf16 v[86:89], v[202:205], v[178:181], v[86:89]
	v_mfma_f32_16x16x32_bf16 v[82:85], v[210:213], v[178:181], v[82:85]
	v_mfma_f32_16x16x32_bf16 v[78:81], v[202:205], v[186:189], v[78:81]
	v_mfma_f32_16x16x32_bf16 v[74:77], v[210:213], v[186:189], v[74:77]
	v_mfma_f32_16x16x32_bf16 v[70:73], v[202:205], v[194:197], v[70:73]
	v_mfma_f32_16x16x32_bf16 v[66:69], v[210:213], v[194:197], v[66:69]
	s_barrier
	ds_read_b128 v[166:169], v141 offset:49152
	ds_read_b128 v[170:173], v141 offset:50176
	ds_read_b128 v[174:177], v141 offset:51200
	ds_read_b128 v[178:181], v141 offset:52224
	ds_read_b128 v[182:185], v141 offset:53248
	ds_read_b128 v[186:189], v141 offset:54272
	ds_read_b128 v[190:193], v141 offset:55296
	ds_read_b128 v[194:197], v141 offset:56320
	s_mov_b32 m0, s56
	s_add_u32 s98, s42, s94
	s_addc_u32 s99, s43, s95
	global_load_lds_dwordx4 v131, s[98:99]
	s_mov_b32 m0, s57
	s_add_u32 s98, s42, s72
	s_addc_u32 s99, s43, s73
	global_load_lds_dwordx4 v131, s[98:99]
	s_barrier
	s_waitcnt lgkmcnt(0)
	s_waitcnt lgkmcnt(0)
	v_mfma_f32_16x16x32_bf16 v[62:65], v[150:153], v[166:169], v[62:65]
	v_mfma_f32_16x16x32_bf16 v[58:61], v[158:161], v[166:169], v[58:61]
	v_mfma_f32_16x16x32_bf16 v[54:57], v[150:153], v[174:177], v[54:57]
	v_mfma_f32_16x16x32_bf16 v[50:53], v[158:161], v[174:177], v[50:53]
	v_mfma_f32_16x16x32_bf16 v[46:49], v[150:153], v[182:185], v[46:49]
	v_mfma_f32_16x16x32_bf16 v[42:45], v[158:161], v[182:185], v[42:45]
	v_mfma_f32_16x16x32_bf16 v[38:41], v[150:153], v[190:193], v[38:41]
	v_mfma_f32_16x16x32_bf16 v[34:37], v[158:161], v[190:193], v[34:37]
	v_mfma_f32_16x16x32_bf16 v[62:65], v[154:157], v[170:173], v[62:65]
	v_mfma_f32_16x16x32_bf16 v[58:61], v[162:165], v[170:173], v[58:61]
	v_mfma_f32_16x16x32_bf16 v[54:57], v[154:157], v[178:181], v[54:57]
	v_mfma_f32_16x16x32_bf16 v[50:53], v[162:165], v[178:181], v[50:53]
	v_mfma_f32_16x16x32_bf16 v[46:49], v[154:157], v[186:189], v[46:49]
	v_mfma_f32_16x16x32_bf16 v[42:45], v[162:165], v[186:189], v[42:45]
	v_mfma_f32_16x16x32_bf16 v[38:41], v[154:157], v[194:197], v[38:41]
	v_mfma_f32_16x16x32_bf16 v[34:37], v[162:165], v[194:197], v[34:37]
	s_barrier
	s_mov_b32 m0, s58
	s_add_u32 s98, s66, s30
	s_addc_u32 s99, s67, s31
	global_load_lds_dwordx4 v131, s[98:99]
	s_mov_b32 m0, s59
	s_add_u32 s98, s66, s44
	s_addc_u32 s99, s67, s45
	global_load_lds_dwordx4 v131, s[98:99]
	s_add_i32 s18, s18, 2
	s_add_u32 vcc_lo, vcc_lo, 0x100
	s_addc_u32 vcc_hi, vcc_hi, 0
	s_cmp_lt_u32 s18, 12
	s_waitcnt vmcnt(10)
	s_barrier
	v_mfma_f32_16x16x32_bf16 v[30:33], v[198:201], v[166:169], v[30:33]
	v_mfma_f32_16x16x32_bf16 v[26:29], v[206:209], v[166:169], v[26:29]
	v_mfma_f32_16x16x32_bf16 v[22:25], v[198:201], v[174:177], v[22:25]
	v_mfma_f32_16x16x32_bf16 v[18:21], v[206:209], v[174:177], v[18:21]
	v_mfma_f32_16x16x32_bf16 v[14:17], v[198:201], v[182:185], v[14:17]
	v_mfma_f32_16x16x32_bf16 v[10:13], v[206:209], v[182:185], v[10:13]
	v_mfma_f32_16x16x32_bf16 v[6:9], v[198:201], v[190:193], v[6:9]
	v_mfma_f32_16x16x32_bf16 v[2:5], v[206:209], v[190:193], v[2:5]
	v_mfma_f32_16x16x32_bf16 v[30:33], v[202:205], v[170:173], v[30:33]
	v_mfma_f32_16x16x32_bf16 v[26:29], v[210:213], v[170:173], v[26:29]
	v_mfma_f32_16x16x32_bf16 v[22:25], v[202:205], v[178:181], v[22:25]
	v_mfma_f32_16x16x32_bf16 v[18:21], v[210:213], v[178:181], v[18:21]
	v_mfma_f32_16x16x32_bf16 v[14:17], v[202:205], v[186:189], v[14:17]
	v_mfma_f32_16x16x32_bf16 v[10:13], v[210:213], v[186:189], v[10:13]
	v_mfma_f32_16x16x32_bf16 v[6:9], v[202:205], v[194:197], v[6:9]
	v_mfma_f32_16x16x32_bf16 v[2:5], v[210:213], v[194:197], v[2:5]
	s_barrier

; #define LDA(dst, b, h) for (int m = 0; m < 4; ++m) for (int k = 0; k < 2; ++k) \
;     dst[m][k] = *reinterpret_cast<const bf16x8*>((char*)SA(b, h) + a_thr + (m * 2 + k) * 1024)
; #define LDB(dst, b, h) for (int n = 0; n < 2; ++n) for (int k = 0; k < 2; ++k) \
;     dst[n][k] = *reinterpret_cast<const bf16x8*>((char*)SB(b, h) + b_thr + (n * 2 + k) * 1024)
; #define MMA(ai, bj, At, Btf) do { __builtin_amdgcn_s_setprio(1); \
;     for (int m = 0; m < 4; ++m) for (int n = 0; n < 2; ++n) for (int k = 0; k < 2; ++k) \
;       acc[ai][bj][m][n] = __builtin_amdgcn_mfma_f32_16x16x32_bf16(Btf[n][k], At[m][k], acc[ai][bj][m][n], 0, 0, 0); \
;     __builtin_amdgcn_s_setprio(0); } while (0)
; #define WAIT_V(n) asm volatile("s_waitcnt vmcnt(" #n ")" ::: "memory")
; #define WAIT_L(n) asm volatile("s_waitcnt lgkmcnt(" #n ")" ::: "memory")
; #define BAR __builtin_amdgcn_s_barrier()
; #define SCHED __builtin_amdgcn_sched_barrier(0)
; template <bool OVL, bool PANEL = false, class Epi>
; __device__ __forceinline__ void gemm_phase(const bf16_t* __restrict__ A, long lda, const bf16_t* __restrict__ Bt, long ldb, int nM, int nN, int K,
;                                            const Epi& epi, bf16_t* shm, int w0) {
;     ...
;   for (int it = 0; have; ++it) {
;     const int brow = pm * BM, bcol = pn * BM;
;     f32x4 acc[2][2][4][2];
; #pragma unroll
;     for (int a0 = 0; a0 < 2; ++a0)
; #pragma unroll
;       for (int a1 = 0; a1 < 2; ++a1)
; #pragma unroll
;         for (int a2 = 0; a2 < 4; ++a2)
; #pragma unroll
;           for (int a3 = 0; a3 < 2; ++a3) acc[a0][a1][a2][a3] = (f32x4){0.f, 0.f, 0.f, 0.f};
;     bf16x8 At[4][2], B0[2][2], B1[2][2];
;     if (wr == 1) BAR;
;     WAIT_V(4); BAR;
;     STAGE(SB(1, 0), Bt, ldb, boff, bcol, 1); STAGE(SA(1, 0), A, lda, aoff, brow, 1); STAGE(SB(1, 1), Bt, ldb, boff, bcol + HALF, 1);
;     WAIT_V(6); BAR;
;     for (int t = 0; t < nt - 2; t += 2) {
;       LDB(B0, 0, 0); SCHED; LDA(At, 0, 0); STAGE(SA(1, 1), A, lda, aoff, brow + HALF, t + 1);
;       WAIT_L(8); BAR; WAIT_L(0); MMA(0, 0, At, B0); BAR; SCHED;
;       LDB(B1, 0, 1); STAGE(SB(0, 0), Bt, ldb, boff, bcol, t + 2);
.LBB0_409:
	s_or_b64 exec, exec, s[0:1]
	s_lshl_b32 s0, s18, 19
	v_readlane_b32 s8, v251, 49
	v_readlane_b32 s9, v251, 50
	s_add_u32 s0, s8, s0
	v_readlane_b32 s10, v251, 51
	v_readlane_b32 s11, v251, 52
	s_addc_u32 s1, s9, 0
	v_mov_b32_e32 v0, v131
	v_add_u32_e32 v144, s96, v130
	s_waitcnt vmcnt(4)
	s_barrier
	s_mov_b64 s[10:11], 0x80
	v_lshl_add_u64 v[2:3], s[0:1], 0, v[0:1]
	v_readfirstlane_b32 s8, v144
	v_add_u32_e32 v145, 0x2000, v144
	v_lshl_add_u64 v[4:5], v[2:3], 0, s[10:11]
	s_mov_b32 m0, s8
	v_readfirstlane_b32 s8, v145
	v_readlane_b32 s40, v252, 20
	v_readlane_b32 s12, v251, 53
	v_readlane_b32 s13, v251, 54
	global_load_lds_dwordx4 v[4:5], off
	s_mov_b32 m0, s8
	s_lshl_b32 s8, s20, 19
	v_readlane_b32 s50, v252, 30
	s_mov_b64 s[12:13], 0x20080
	v_readlane_b32 s51, v252, 31
	s_add_u32 s8, s50, s8
	v_lshl_add_u64 v[2:3], v[2:3], 0, s[12:13]
	s_addc_u32 s9, s51, 0
	v_mov_b32_e32 v0, v131
	global_load_lds_dwordx4 v[2:3], off
	v_add_u32_e32 v146, 0x8000, v134
	v_lshl_add_u64 v[2:3], s[8:9], 0, v[0:1]
	v_lshl_add_u64 v[4:5], v[2:3], 0, s[10:11]
	v_readfirstlane_b32 s10, v146
	v_add_u32_e32 v147, 0xa000, v134
	s_mov_b32 m0, s10
	v_readfirstlane_b32 s10, v147
	global_load_lds_dwordx4 v[4:5], off
	v_lshl_add_u64 v[2:3], v[2:3], 0, s[12:13]
	s_mov_b32 m0, s10
	v_mov_b32_e32 v0, v131
	v_add_u32_e32 v148, s75, v130
	global_load_lds_dwordx4 v[2:3], off
	s_mov_b64 s[24:25], 0x40080
	v_lshl_add_u64 v[2:3], s[0:1], 0, v[0:1]
	v_readfirstlane_b32 s10, v148
	v_add_u32_e32 v149, 0x2000, v148
	v_lshl_add_u64 v[4:5], v[2:3], 0, s[24:25]
	s_mov_b32 m0, s10
	v_readfirstlane_b32 s10, v149
	global_load_lds_dwordx4 v[4:5], off
	v_lshl_add_u64 v[2:3], v[2:3], 0, s[36:37]
	s_mov_b32 m0, s10
	s_mov_b32 s21, -2
	global_load_lds_dwordx4 v[2:3], off
	s_waitcnt vmcnt(6)
	s_mov_b64 s[10:11], 0
	s_waitcnt vmcnt(0)
	s_waitcnt lgkmcnt(0)
	s_mov_b64 s[26:27], 0x40180
	s_mov_b64 s[28:29], 0x60180
	v_readlane_b32 s14, v251, 55
	v_readlane_b32 s15, v251, 56
	v_readlane_b32 s41, v252, 21
	v_readlane_b32 s42, v252, 22
	v_readlane_b32 s43, v252, 23
	v_readlane_b32 s44, v252, 24
	v_readlane_b32 s45, v252, 25
	v_readlane_b32 s46, v252, 26
	v_readlane_b32 s47, v252, 27
	v_readlane_b32 s48, v252, 28
	v_readlane_b32 s49, v252, 29
	v_readlane_b32 s52, v252, 32
	v_readlane_b32 s53, v252, 33
	v_readlane_b32 s54, v252, 34
	v_readlane_b32 s55, v252, 35
	s_barrier
	v_add_u32_e32 v220, s2, v140
	v_readfirstlane_b32 s16, v134
	s_add_u32 s16, s16, 0xc000
	v_readfirstlane_b32 s23, v134
	s_add_u32 s23, s23, 0xe000
	v_add_u32_e32 v221, s33, v140
	v_readfirstlane_b32 s30, v132
	v_readfirstlane_b32 s31, v133
	v_readfirstlane_b32 s32, v134
	v_readfirstlane_b32 s40, v135
	v_readfirstlane_b32 s41, v136
	v_readfirstlane_b32 s42, v137
	v_add_u32_e32 v222, s96, v140
	v_readfirstlane_b32 s43, v138
	v_readfirstlane_b32 s44, v139
	v_add_u32_e32 v223, s75, v140
	v_readfirstlane_b32 s45, v144
	v_readfirstlane_b32 s46, v145
	v_readfirstlane_b32 s47, v146
	v_readfirstlane_b32 s48, v147
	v_readfirstlane_b32 s49, v148
	v_readfirstlane_b32 s50, v149
	v_add_u32_e32 v150, 0xc000, v134
	v_add_u32_e32 v151, 0xe000, v134
	ds_read_b128 v[152:155], v220
	ds_read_b128 v[156:159], v220 offset:1024
	ds_read_b128 v[160:163], v220 offset:2048
	ds_read_b128 v[164:167], v220 offset:3072
	s_add_u32 s12, s8, s10
	s_addc_u32 s13, s9, s11
	ds_read_b128 v[168:171], v143
	ds_read_b128 v[172:175], v143 offset:1024
	ds_read_b128 v[176:179], v143 offset:2048
	ds_read_b128 v[180:183], v143 offset:3072
	ds_read_b128 v[184:187], v143 offset:4096
	ds_read_b128 v[188:191], v143 offset:5120
	ds_read_b128 v[192:195], v143 offset:6144
	ds_read_b128 v[196:199], v143 offset:7168
	s_mov_b32 m0, s16
	s_add_u32 s98, s12, s24
	s_addc_u32 s99, s13, s25
	global_load_lds_dwordx4 v131, s[98:99]
	s_mov_b32 m0, s23
	s_add_u32 s98, s12, s36
	s_addc_u32 s99, s13, s37
	global_load_lds_dwordx4 v131, s[98:99]
	s_waitcnt lgkmcnt(8)
	s_waitcnt vmcnt(10)
	s_barrier
	s_waitcnt lgkmcnt(0)
	s_waitcnt lgkmcnt(0)
	v_mfma_f32_16x16x32_bf16 v[126:129], v[152:155], v[168:171], 0
	v_mfma_f32_16x16x32_bf16 v[122:125], v[160:163], v[168:171], 0
	v_mfma_f32_16x16x32_bf16 v[118:121], v[152:155], v[176:179], 0
	v_mfma_f32_16x16x32_bf16 v[114:117], v[160:163], v[176:179], 0
	v_mfma_f32_16x16x32_bf16 v[110:113], v[152:155], v[184:187], 0
	v_mfma_f32_16x16x32_bf16 v[106:109], v[160:163], v[184:187], 0
	v_mfma_f32_16x16x32_bf16 v[102:105], v[152:155], v[192:195], 0
	v_mfma_f32_16x16x32_bf16 v[98:101], v[160:163], v[192:195], 0
	v_mfma_f32_16x16x32_bf16 v[126:129], v[156:159], v[172:175], v[126:129]
	v_mfma_f32_16x16x32_bf16 v[122:125], v[164:167], v[172:175], v[122:125]
	v_mfma_f32_16x16x32_bf16 v[118:121], v[156:159], v[180:183], v[118:121]
	v_mfma_f32_16x16x32_bf16 v[114:117], v[164:167], v[180:183], v[114:117]
	v_mfma_f32_16x16x32_bf16 v[110:113], v[156:159], v[188:191], v[110:113]
	v_mfma_f32_16x16x32_bf16 v[106:109], v[164:167], v[188:191], v[106:109]
	v_mfma_f32_16x16x32_bf16 v[102:105], v[156:159], v[196:199], v[102:105]
	v_mfma_f32_16x16x32_bf16 v[98:101], v[164:167], v[196:199], v[98:101]
	s_barrier
	s_add_u32 s14, s0, s10
	ds_read_b128 v[200:203], v221
	ds_read_b128 v[204:207], v221 offset:1024
	ds_read_b128 v[208:211], v221 offset:2048
	ds_read_b128 v[212:215], v221 offset:3072
	s_addc_u32 s15, s1, s11
	s_mov_b32 m0, s30
	s_add_u32 s98, s14, s34
	s_addc_u32 s99, s15, s35
	global_load_lds_dwordx4 v131, s[98:99]
	s_mov_b32 m0, s31
	s_add_u32 s98, s14, s64
	s_addc_u32 s99, s15, s65
	global_load_lds_dwordx4 v131, s[98:99]
	s_waitcnt vmcnt(10)
	s_barrier
; #define LDA(dst, b, h) for (int m = 0; m < 4; ++m) for (int k = 0; k < 2; ++k) \
;     dst[m][k] = *reinterpret_cast<const bf16x8*>((char*)SA(b, h) + a_thr + (m * 2 + k) * 1024)
; #define LDB(dst, b, h) for (int n = 0; n < 2; ++n) for (int k = 0; k < 2; ++k) \
;     dst[n][k] = *reinterpret_cast<const bf16x8*>((char*)SB(b, h) + b_thr + (n * 2 + k) * 1024)
; #define MMA(ai, bj, At, Btf) do { __builtin_amdgcn_s_setprio(1); \
;     for (int m = 0; m < 4; ++m) for (int n = 0; n < 2; ++n) for (int k = 0; k < 2; ++k) \
;       acc[ai][bj][m][n] = __builtin_amdgcn_mfma_f32_16x16x32_bf16(Btf[n][k], At[m][k], acc[ai][bj][m][n], 0, 0, 0); \
;     __builtin_amdgcn_s_setprio(0); } while (0)
; #define WAIT_V(n) asm volatile("s_waitcnt vmcnt(" #n ")" ::: "memory")
; #define WAIT_L(n) asm volatile("s_waitcnt lgkmcnt(" #n ")" ::: "memory")
; #define BAR __builtin_amdgcn_s_barrier()
; #define SCHED __builtin_amdgcn_sched_barrier(0)
; template <bool OVL, bool PANEL = false, class Epi>
; __device__ __forceinline__ void gemm_phase(const bf16_t* __restrict__ A, long lda, const bf16_t* __restrict__ Bt, long ldb, int nM, int nN, int K,
;                                            const Epi& epi, bf16_t* shm, int w0) {
;     ...
;       BAR; WAIT_L(0); MMA(0, 1, At, B1); BAR;
;       LDA(At, 0, 1); STAGE(SA(0, 0), A, lda, aoff, brow, t + 2);
;       BAR; WAIT_L(0); MMA(1, 0, At, B0); BAR; SCHED;
;       STAGE(SB(0, 1), Bt, ldb, boff, bcol + HALF, t + 2);
;       WAIT_V(6); BAR; MMA(1, 1, At, B1); BAR;
;       LDB(B0, 1, 0); SCHED; LDA(At, 1, 0); STAGE(SA(0, 1), A, lda, aoff, brow + HALF, t + 2);
;       WAIT_L(8); BAR; WAIT_L(0); MMA(0, 0, At, B0); BAR; SCHED;
	s_waitcnt lgkmcnt(0)
	s_waitcnt lgkmcnt(0)
	v_mfma_f32_16x16x32_bf16 v[94:97], v[200:203], v[168:171], 0
	v_mfma_f32_16x16x32_bf16 v[90:93], v[208:211], v[168:171], 0
	v_mfma_f32_16x16x32_bf16 v[86:89], v[200:203], v[176:179], 0
	v_mfma_f32_16x16x32_bf16 v[82:85], v[208:211], v[176:179], 0
	v_mfma_f32_16x16x32_bf16 v[78:81], v[200:203], v[184:187], 0
	v_mfma_f32_16x16x32_bf16 v[74:77], v[208:211], v[184:187], 0
	v_mfma_f32_16x16x32_bf16 v[70:73], v[200:203], v[192:195], 0
	v_mfma_f32_16x16x32_bf16 v[66:69], v[208:211], v[192:195], 0
	v_mfma_f32_16x16x32_bf16 v[94:97], v[204:207], v[172:175], v[94:97]
	v_mfma_f32_16x16x32_bf16 v[90:93], v[212:215], v[172:175], v[90:93]
	v_mfma_f32_16x16x32_bf16 v[86:89], v[204:207], v[180:183], v[86:89]
	v_mfma_f32_16x16x32_bf16 v[82:85], v[212:215], v[180:183], v[82:85]
	v_mfma_f32_16x16x32_bf16 v[78:81], v[204:207], v[188:191], v[78:81]
	v_mfma_f32_16x16x32_bf16 v[74:77], v[212:215], v[188:191], v[74:77]
	v_mfma_f32_16x16x32_bf16 v[70:73], v[204:207], v[196:199], v[70:73]
	v_mfma_f32_16x16x32_bf16 v[66:69], v[212:215], v[196:199], v[66:69]
	s_barrier
	ds_read_b128 v[168:171], v143 offset:16384
	ds_read_b128 v[172:175], v143 offset:17408
	ds_read_b128 v[176:179], v143 offset:18432
	ds_read_b128 v[180:183], v143 offset:19456
	ds_read_b128 v[184:187], v143 offset:20480
	ds_read_b128 v[188:191], v143 offset:21504
	ds_read_b128 v[192:195], v143 offset:22528
	ds_read_b128 v[196:199], v143 offset:23552
	s_mov_b32 m0, s32
	s_add_u32 s98, s12, s34
	s_addc_u32 s99, s13, s35
	global_load_lds_dwordx4 v131, s[98:99]
	s_mov_b32 m0, s40
	s_add_u32 s98, s12, s64
	s_addc_u32 s99, s13, s65
	global_load_lds_dwordx4 v131, s[98:99]
	s_barrier
	s_waitcnt lgkmcnt(0)
	s_waitcnt lgkmcnt(0)
	v_mfma_f32_16x16x32_bf16 v[62:65], v[152:155], v[168:171], 0
	v_mfma_f32_16x16x32_bf16 v[58:61], v[160:163], v[168:171], 0
	v_mfma_f32_16x16x32_bf16 v[54:57], v[152:155], v[176:179], 0
	v_mfma_f32_16x16x32_bf16 v[50:53], v[160:163], v[176:179], 0
	v_mfma_f32_16x16x32_bf16 v[46:49], v[152:155], v[184:187], 0
	v_mfma_f32_16x16x32_bf16 v[42:45], v[160:163], v[184:187], 0
	v_mfma_f32_16x16x32_bf16 v[38:41], v[152:155], v[192:195], 0
	v_mfma_f32_16x16x32_bf16 v[34:37], v[160:163], v[192:195], 0
	v_mfma_f32_16x16x32_bf16 v[62:65], v[156:159], v[172:175], v[62:65]
	v_mfma_f32_16x16x32_bf16 v[58:61], v[164:167], v[172:175], v[58:61]
	v_mfma_f32_16x16x32_bf16 v[54:57], v[156:159], v[180:183], v[54:57]
	v_mfma_f32_16x16x32_bf16 v[50:53], v[164:167], v[180:183], v[50:53]
	v_mfma_f32_16x16x32_bf16 v[46:49], v[156:159], v[188:191], v[46:49]
	v_mfma_f32_16x16x32_bf16 v[42:45], v[164:167], v[188:191], v[42:45]
	v_mfma_f32_16x16x32_bf16 v[38:41], v[156:159], v[196:199], v[38:41]
	v_mfma_f32_16x16x32_bf16 v[34:37], v[164:167], v[196:199], v[34:37]
	s_barrier
	s_mov_b32 m0, s41
	s_add_u32 s98, s14, s68
	s_addc_u32 s99, s15, s69
	global_load_lds_dwordx4 v131, s[98:99]
	s_mov_b32 m0, s42
	s_add_u32 s98, s14, s70
	s_addc_u32 s99, s15, s71
	global_load_lds_dwordx4 v131, s[98:99]
	s_waitcnt vmcnt(10)
	s_barrier
	v_mfma_f32_16x16x32_bf16 v[30:33], v[200:203], v[168:171], 0
	v_mfma_f32_16x16x32_bf16 v[26:29], v[208:211], v[168:171], 0
	v_mfma_f32_16x16x32_bf16 v[22:25], v[200:203], v[176:179], 0
	v_mfma_f32_16x16x32_bf16 v[18:21], v[208:211], v[176:179], 0
	v_mfma_f32_16x16x32_bf16 v[14:17], v[200:203], v[184:187], 0
	v_mfma_f32_16x16x32_bf16 v[10:13], v[208:211], v[184:187], 0
	v_mfma_f32_16x16x32_bf16 v[6:9], v[200:203], v[192:195], 0
	v_mfma_f32_16x16x32_bf16 v[2:5], v[208:211], v[192:195], 0
	v_mfma_f32_16x16x32_bf16 v[30:33], v[204:207], v[172:175], v[30:33]
	v_mfma_f32_16x16x32_bf16 v[26:29], v[212:215], v[172:175], v[26:29]
	v_mfma_f32_16x16x32_bf16 v[22:25], v[204:207], v[180:183], v[22:25]
	v_mfma_f32_16x16x32_bf16 v[18:21], v[212:215], v[180:183], v[18:21]
	v_mfma_f32_16x16x32_bf16 v[14:17], v[204:207], v[188:191], v[14:17]
	v_mfma_f32_16x16x32_bf16 v[10:13], v[212:215], v[188:191], v[10:13]
	v_mfma_f32_16x16x32_bf16 v[6:9], v[204:207], v[196:199], v[6:9]
	v_mfma_f32_16x16x32_bf16 v[2:5], v[212:215], v[196:199], v[2:5]
	s_barrier
	ds_read_b128 v[152:155], v222
	ds_read_b128 v[156:159], v222 offset:1024
	ds_read_b128 v[160:163], v222 offset:2048
	ds_read_b128 v[164:167], v222 offset:3072
	ds_read_b128 v[168:171], v143 offset:32768
	ds_read_b128 v[172:175], v143 offset:33792
	ds_read_b128 v[176:179], v143 offset:34816
	ds_read_b128 v[180:183], v143 offset:35840
	ds_read_b128 v[184:187], v143 offset:36864
	ds_read_b128 v[188:191], v143 offset:37888
	ds_read_b128 v[192:195], v143 offset:38912
	ds_read_b128 v[196:199], v143 offset:39936
	s_mov_b32 m0, s43
	s_add_u32 s98, s12, s68
	s_addc_u32 s99, s13, s69
	global_load_lds_dwordx4 v131, s[98:99]
	s_mov_b32 m0, s44
	s_add_u32 s98, s12, s70
	s_addc_u32 s99, s13, s71
	global_load_lds_dwordx4 v131, s[98:99]
	s_waitcnt lgkmcnt(8)
	s_waitcnt vmcnt(10)
	s_barrier
; #define LDA(dst, b, h) for (int m = 0; m < 4; ++m) for (int k = 0; k < 2; ++k) \
;     dst[m][k] = *reinterpret_cast<const bf16x8*>((char*)SA(b, h) + a_thr + (m * 2 + k) * 1024)
; #define LDB(dst, b, h) for (int n = 0; n < 2; ++n) for (int k = 0; k < 2; ++k) \
;     dst[n][k] = *reinterpret_cast<const bf16x8*>((char*)SB(b, h) + b_thr + (n * 2 + k) * 1024)
; #define MMA(ai, bj, At, Btf) do { __builtin_amdgcn_s_setprio(1); \
;     for (int m = 0; m < 4; ++m) for (int n = 0; n < 2; ++n) for (int k = 0; k < 2; ++k) \
;       acc[ai][bj][m][n] = __builtin_amdgcn_mfma_f32_16x16x32_bf16(Btf[n][k], At[m][k], acc[ai][bj][m][n], 0, 0, 0); \
;     __builtin_amdgcn_s_setprio(0); } while (0)
; #define WAIT_V(n) asm volatile("s_waitcnt vmcnt(" #n ")" ::: "memory")
; #define WAIT_L(n) asm volatile("s_waitcnt lgkmcnt(" #n ")" ::: "memory")
; #define BAR __builtin_amdgcn_s_barrier()
; #define SCHED __builtin_amdgcn_sched_barrier(0)
; template <bool OVL, bool PANEL = false, class Epi>
; __device__ __forceinline__ void gemm_phase(const bf16_t* __restrict__ A, long lda, const bf16_t* __restrict__ Bt, long ldb, int nM, int nN, int K,
;                                            const Epi& epi, bf16_t* shm, int w0) {
;     ...
;       WAIT_L(8); BAR; WAIT_L(0); MMA(0, 0, At, B0); BAR; SCHED;
;       LDB(B1, 1, 1); STAGE(SB(1, 0), Bt, ldb, boff, bcol, t + 3);
;       BAR; WAIT_L(0); MMA(0, 1, At, B1); BAR;
;       LDA(At, 1, 1); STAGE(SA(1, 0), A, lda, aoff, brow, t + 3);
;       BAR; WAIT_L(0); MMA(1, 0, At, B0); BAR; SCHED;
;       STAGE(SB(1, 1), Bt, ldb, boff, bcol + HALF, t + 3);
;       WAIT_V(6); BAR; MMA(1, 1, At, B1); BAR;
	s_waitcnt lgkmcnt(0)
	s_waitcnt lgkmcnt(0)
	v_mfma_f32_16x16x32_bf16 v[126:129], v[152:155], v[168:171], v[126:129]
	v_mfma_f32_16x16x32_bf16 v[122:125], v[160:163], v[168:171], v[122:125]
	v_mfma_f32_16x16x32_bf16 v[118:121], v[152:155], v[176:179], v[118:121]
	v_mfma_f32_16x16x32_bf16 v[114:117], v[160:163], v[176:179], v[114:117]
	v_mfma_f32_16x16x32_bf16 v[110:113], v[152:155], v[184:187], v[110:113]
	v_mfma_f32_16x16x32_bf16 v[106:109], v[160:163], v[184:187], v[106:109]
	v_mfma_f32_16x16x32_bf16 v[102:105], v[152:155], v[192:195], v[102:105]
	v_mfma_f32_16x16x32_bf16 v[98:101], v[160:163], v[192:195], v[98:101]
	v_mfma_f32_16x16x32_bf16 v[126:129], v[156:159], v[172:175], v[126:129]
	v_mfma_f32_16x16x32_bf16 v[122:125], v[164:167], v[172:175], v[122:125]
	v_mfma_f32_16x16x32_bf16 v[118:121], v[156:159], v[180:183], v[118:121]
	v_mfma_f32_16x16x32_bf16 v[114:117], v[164:167], v[180:183], v[114:117]
	v_mfma_f32_16x16x32_bf16 v[110:113], v[156:159], v[188:191], v[110:113]
	v_mfma_f32_16x16x32_bf16 v[106:109], v[164:167], v[188:191], v[106:109]
	v_mfma_f32_16x16x32_bf16 v[102:105], v[156:159], v[196:199], v[102:105]
	v_mfma_f32_16x16x32_bf16 v[98:101], v[164:167], v[196:199], v[98:101]
	s_barrier
	ds_read_b128 v[200:203], v223
	ds_read_b128 v[204:207], v223 offset:1024
	ds_read_b128 v[208:211], v223 offset:2048
	ds_read_b128 v[212:215], v223 offset:3072
	s_mov_b32 m0, s45
	s_add_u32 s98, s14, s94
	s_addc_u32 s99, s15, s95
	global_load_lds_dwordx4 v131, s[98:99]
	s_mov_b32 m0, s46
	s_add_u32 s98, s14, s72
	s_addc_u32 s99, s15, s73
	global_load_lds_dwordx4 v131, s[98:99]
	s_waitcnt vmcnt(10)
	s_barrier
	s_waitcnt lgkmcnt(0)
	s_waitcnt lgkmcnt(0)
	v_mfma_f32_16x16x32_bf16 v[94:97], v[200:203], v[168:171], v[94:97]
	v_mfma_f32_16x16x32_bf16 v[90:93], v[208:211], v[168:171], v[90:93]
	v_mfma_f32_16x16x32_bf16 v[86:89], v[200:203], v[176:179], v[86:89]
	v_mfma_f32_16x16x32_bf16 v[82:85], v[208:211], v[176:179], v[82:85]
	v_mfma_f32_16x16x32_bf16 v[78:81], v[200:203], v[184:187], v[78:81]
	v_mfma_f32_16x16x32_bf16 v[74:77], v[208:211], v[184:187], v[74:77]
	v_mfma_f32_16x16x32_bf16 v[70:73], v[200:203], v[192:195], v[70:73]
	v_mfma_f32_16x16x32_bf16 v[66:69], v[208:211], v[192:195], v[66:69]
	v_mfma_f32_16x16x32_bf16 v[94:97], v[204:207], v[172:175], v[94:97]
	v_mfma_f32_16x16x32_bf16 v[90:93], v[212:215], v[172:175], v[90:93]
	v_mfma_f32_16x16x32_bf16 v[86:89], v[204:207], v[180:183], v[86:89]
	v_mfma_f32_16x16x32_bf16 v[82:85], v[212:215], v[180:183], v[82:85]
	v_mfma_f32_16x16x32_bf16 v[78:81], v[204:207], v[188:191], v[78:81]
	v_mfma_f32_16x16x32_bf16 v[74:77], v[212:215], v[188:191], v[74:77]
	v_mfma_f32_16x16x32_bf16 v[70:73], v[204:207], v[196:199], v[70:73]
	v_mfma_f32_16x16x32_bf16 v[66:69], v[212:215], v[196:199], v[66:69]
	s_barrier
	ds_read_b128 v[168:171], v143 offset:49152
	ds_read_b128 v[172:175], v143 offset:50176
	ds_read_b128 v[176:179], v143 offset:51200
	ds_read_b128 v[180:183], v143 offset:52224
	ds_read_b128 v[184:187], v143 offset:53248
	ds_read_b128 v[188:191], v143 offset:54272
	ds_read_b128 v[192:195], v143 offset:55296
	ds_read_b128 v[196:199], v143 offset:56320
	s_mov_b32 m0, s47
	s_add_u32 s98, s12, s94
	s_addc_u32 s99, s13, s95
	global_load_lds_dwordx4 v131, s[98:99]
	s_mov_b32 m0, s48
	s_add_u32 s98, s12, s72
	s_addc_u32 s99, s13, s73
	global_load_lds_dwordx4 v131, s[98:99]
	s_barrier
	s_waitcnt lgkmcnt(0)
	s_waitcnt lgkmcnt(0)
	v_mfma_f32_16x16x32_bf16 v[62:65], v[152:155], v[168:171], v[62:65]
	v_mfma_f32_16x16x32_bf16 v[58:61], v[160:163], v[168:171], v[58:61]
	v_mfma_f32_16x16x32_bf16 v[54:57], v[152:155], v[176:179], v[54:57]
	v_mfma_f32_16x16x32_bf16 v[50:53], v[160:163], v[176:179], v[50:53]
	v_mfma_f32_16x16x32_bf16 v[46:49], v[152:155], v[184:187], v[46:49]
	v_mfma_f32_16x16x32_bf16 v[42:45], v[160:163], v[184:187], v[42:45]
	v_mfma_f32_16x16x32_bf16 v[38:41], v[152:155], v[192:195], v[38:41]
	v_mfma_f32_16x16x32_bf16 v[34:37], v[160:163], v[192:195], v[34:37]
	v_mfma_f32_16x16x32_bf16 v[62:65], v[156:159], v[172:175], v[62:65]
	v_mfma_f32_16x16x32_bf16 v[58:61], v[164:167], v[172:175], v[58:61]
	v_mfma_f32_16x16x32_bf16 v[54:57], v[156:159], v[180:183], v[54:57]
	v_mfma_f32_16x16x32_bf16 v[50:53], v[164:167], v[180:183], v[50:53]
	v_mfma_f32_16x16x32_bf16 v[46:49], v[156:159], v[188:191], v[46:49]
	v_mfma_f32_16x16x32_bf16 v[42:45], v[164:167], v[188:191], v[42:45]
	v_mfma_f32_16x16x32_bf16 v[38:41], v[156:159], v[196:199], v[38:41]
	v_mfma_f32_16x16x32_bf16 v[34:37], v[164:167], v[196:199], v[34:37]
	s_barrier
	s_mov_b32 m0, s49
	s_add_u32 s98, s14, s26
	s_addc_u32 s99, s15, s27
	global_load_lds_dwordx4 v131, s[98:99]
	s_mov_b32 m0, s50
	s_add_u32 s98, s14, s28
	s_addc_u32 s99, s15, s29
	global_load_lds_dwordx4 v131, s[98:99]
	s_add_i32 s21, s21, 2
	s_add_u32 s10, s10, 0x100
	s_addc_u32 s11, s11, 0
	s_cmp_lt_u32 s21, 12
	s_waitcnt vmcnt(10)
	s_barrier
	v_mfma_f32_16x16x32_bf16 v[30:33], v[200:203], v[168:171], v[30:33]
	v_mfma_f32_16x16x32_bf16 v[26:29], v[208:211], v[168:171], v[26:29]
	v_mfma_f32_16x16x32_bf16 v[22:25], v[200:203], v[176:179], v[22:25]
	v_mfma_f32_16x16x32_bf16 v[18:21], v[208:211], v[176:179], v[18:21]
	v_mfma_f32_16x16x32_bf16 v[14:17], v[200:203], v[184:187], v[14:17]
	v_mfma_f32_16x16x32_bf16 v[10:13], v[208:211], v[184:187], v[10:13]
	v_mfma_f32_16x16x32_bf16 v[6:9], v[200:203], v[192:195], v[6:9]
	v_mfma_f32_16x16x32_bf16 v[2:5], v[208:211], v[192:195], v[2:5]
	v_mfma_f32_16x16x32_bf16 v[30:33], v[204:207], v[172:175], v[30:33]
	v_mfma_f32_16x16x32_bf16 v[26:29], v[212:215], v[172:175], v[26:29]
	v_mfma_f32_16x16x32_bf16 v[22:25], v[204:207], v[180:183], v[22:25]
	v_mfma_f32_16x16x32_bf16 v[18:21], v[212:215], v[180:183], v[18:21]
	v_mfma_f32_16x16x32_bf16 v[14:17], v[204:207], v[188:191], v[14:17]
	v_mfma_f32_16x16x32_bf16 v[10:13], v[212:215], v[188:191], v[10:13]
	v_mfma_f32_16x16x32_bf16 v[6:9], v[204:207], v[196:199], v[6:9]
	v_mfma_f32_16x16x32_bf16 v[2:5], v[212:215], v[196:199], v[2:5]
	s_barrier

; #define LDA(dst, b, h) for (int m = 0; m < 4; ++m) for (int k = 0; k < 2; ++k) \
;     dst[m][k] = *reinterpret_cast<const bf16x8*>((char*)SA(b, h) + a_thr + (m * 2 + k) * 1024)
; #define LDB(dst, b, h) for (int n = 0; n < 2; ++n) for (int k = 0; k < 2; ++k) \
;     dst[n][k] = *reinterpret_cast<const bf16x8*>((char*)SB(b, h) + b_thr + (n * 2 + k) * 1024)
; #define MMA(ai, bj, At, Btf) do { __builtin_amdgcn_s_setprio(1); \
;     for (int m = 0; m < 4; ++m) for (int n = 0; n < 2; ++n) for (int k = 0; k < 2; ++k) \
;       acc[ai][bj][m][n] = __builtin_amdgcn_mfma_f32_16x16x32_bf16(Btf[n][k], At[m][k], acc[ai][bj][m][n], 0, 0, 0); \
;     __builtin_amdgcn_s_setprio(0); } while (0)
; #define WAIT_V(n) asm volatile("s_waitcnt vmcnt(" #n ")" ::: "memory")
; #define WAIT_L(n) asm volatile("s_waitcnt lgkmcnt(" #n ")" ::: "memory")
; #define BAR __builtin_amdgcn_s_barrier()
; #define SCHED __builtin_amdgcn_sched_barrier(0)
; template <bool OVL, bool PANEL = false, class Epi>
; __device__ __forceinline__ void gemm_phase(const bf16_t* __restrict__ A, long lda, const bf16_t* __restrict__ Bt, long ldb, int nM, int nN, int K,
;                                            const Epi& epi, bf16_t* shm, int w0) {
;     ...
;   for (int it = 0; have; ++it) {
;     const int brow = pm * BM, bcol = pn * BM;
;     f32x4 acc[2][2][4][2];
; #pragma unroll
;     for (int a0 = 0; a0 < 2; ++a0)
; #pragma unroll
;       for (int a1 = 0; a1 < 2; ++a1)
; #pragma unroll
;         for (int a2 = 0; a2 < 4; ++a2)
; #pragma unroll
;           for (int a3 = 0; a3 < 2; ++a3) acc[a0][a1][a2][a3] = (f32x4){0.f, 0.f, 0.f, 0.f};
;     bf16x8 At[4][2], B0[2][2], B1[2][2];
;     if (wr == 1) BAR;
;     WAIT_V(4); BAR;
;     STAGE(SB(1, 0), Bt, ldb, boff, bcol, 1); STAGE(SA(1, 0), A, lda, aoff, brow, 1); STAGE(SB(1, 1), Bt, ldb, boff, bcol + HALF, 1);
;     WAIT_V(6); BAR;
;     for (int t = 0; t < nt - 2; t += 2) {
;       LDB(B0, 0, 0); SCHED; LDA(At, 0, 0); STAGE(SA(1, 1), A, lda, aoff, brow + HALF, t + 1);
;       WAIT_L(8); BAR; WAIT_L(0); MMA(0, 0, At, B0); BAR; SCHED;
;       LDB(B1, 0, 1); STAGE(SB(0, 0), Bt, ldb, boff, bcol, t + 2);
.LBB0_471:
	s_or_b64 exec, exec, s[0:1]
	s_lshl_b32 s2, s25, 18
	v_readlane_b32 s44, v252, 3
	s_lshl_b32 s82, s4, 8
	s_lshl_b64 s[0:1], s[2:3], 1
	v_readlane_b32 s58, v252, 17
	v_readlane_b32 s59, v252, 18
	s_add_u32 s6, s58, s0
	s_addc_u32 s7, s59, s1
	v_mov_b32_e32 v0, v221
	v_add_u32_e32 v130, s96, v220
	s_waitcnt vmcnt(4)
	s_barrier
	v_readlane_b32 s45, v252, 4
	v_readlane_b32 s46, v252, 5
	v_readlane_b32 s47, v252, 6
	v_readlane_b32 s48, v252, 7
	v_readlane_b32 s49, v252, 8
	v_readlane_b32 s50, v252, 9
	v_readlane_b32 s51, v252, 10
	v_readlane_b32 s52, v252, 11
	v_readlane_b32 s53, v252, 12
	v_readlane_b32 s54, v252, 13
	v_readlane_b32 s55, v252, 14
	v_readlane_b32 s56, v252, 15
	v_readlane_b32 s57, v252, 16
	s_mov_b64 s[12:13], 0x80
	v_lshl_add_u64 v[2:3], s[6:7], 0, v[0:1]
	v_readfirstlane_b32 s0, v130
	v_add_u32_e32 v131, 0x2000, v130
	v_lshl_add_u64 v[4:5], v[2:3], 0, s[12:13]
	s_mov_b32 m0, s0
	v_readfirstlane_b32 s0, v131
	s_ashr_i32 s83, s82, 31
	v_readlane_b32 s44, v252, 20
	global_load_lds_dwordx4 v[4:5], off
	s_mov_b32 m0, s0
	s_lshl_b64 s[0:1], s[82:83], 11
	v_readlane_b32 s50, v252, 26
	s_mov_b64 s[14:15], 0x20080
	v_readlane_b32 s51, v252, 27
	s_add_u32 s8, s50, s0
	v_lshl_add_u64 v[2:3], v[2:3], 0, s[14:15]
	s_addc_u32 s9, s51, s1
	v_mov_b32_e32 v0, v221
	v_add_u32_e32 v132, 0x8000, v234
	global_load_lds_dwordx4 v[2:3], off
	v_readfirstlane_b32 s0, v132
	v_lshl_add_u64 v[2:3], s[8:9], 0, v[0:1]
	v_add_u32_e32 v133, 0xa000, v234
	v_lshl_add_u64 v[4:5], v[2:3], 0, s[12:13]
	s_mov_b32 m0, s0
	v_readfirstlane_b32 s0, v133
	global_load_lds_dwordx4 v[4:5], off
	v_lshl_add_u64 v[2:3], v[2:3], 0, s[14:15]
	s_mov_b32 m0, s0
	v_mov_b32_e32 v0, v221
	v_add_u32_e32 v134, s75, v220
	global_load_lds_dwordx4 v[2:3], off
	s_mov_b64 s[12:13], 0x40080
	v_lshl_add_u64 v[2:3], s[6:7], 0, v[0:1]
	v_readfirstlane_b32 s0, v134
	v_add_u32_e32 v135, 0x2000, v134
	v_lshl_add_u64 v[4:5], v[2:3], 0, s[12:13]
	s_mov_b32 m0, s0
	v_readfirstlane_b32 s0, v135
	global_load_lds_dwordx4 v[4:5], off
	v_lshl_add_u64 v[2:3], v[2:3], 0, s[36:37]
	s_mov_b32 m0, s0
	s_mov_b32 s2, -2
	global_load_lds_dwordx4 v[2:3], off
	s_waitcnt vmcnt(6)
	s_mov_b64 s[80:81], 0
	s_waitcnt vmcnt(0)
	s_waitcnt lgkmcnt(0)
	s_mov_b64 s[14:15], 0x40180
	s_mov_b64 s[18:19], 0x60180
	v_readlane_b32 s45, v252, 21
	v_readlane_b32 s46, v252, 22
	v_readlane_b32 s47, v252, 23
	v_readlane_b32 s48, v252, 24
	v_readlane_b32 s49, v252, 25
	v_readlane_b32 s52, v252, 28
	v_readlane_b32 s53, v252, 29
	v_readlane_b32 s54, v252, 30
	v_readlane_b32 s55, v252, 31
	v_readlane_b32 s56, v252, 32
	v_readlane_b32 s57, v252, 33
	v_readlane_b32 s58, v252, 34
	v_readlane_b32 s59, v252, 35
	s_barrier
	v_add_u32_e32 v206, s20, v240
	v_readfirstlane_b32 s16, v234
	s_add_u32 s16, s16, 0xc000
	v_readfirstlane_b32 s32, v234
	s_add_u32 s32, s32, 0xe000
	v_add_u32_e32 v207, s33, v240
	v_readfirstlane_b32 s44, v222
	v_readfirstlane_b32 s45, v223
	v_readfirstlane_b32 s46, v234
	v_readfirstlane_b32 s47, v235
	v_readfirstlane_b32 s48, v236
	v_readfirstlane_b32 s49, v237
	v_add_u32_e32 v208, s96, v240
	v_readfirstlane_b32 s50, v238
	v_readfirstlane_b32 s51, v239
	v_add_u32_e32 v209, s75, v240
	v_readfirstlane_b32 s52, v130
	v_readfirstlane_b32 s53, v131
	v_readfirstlane_b32 s54, v132
	v_readfirstlane_b32 s55, v133
	v_readfirstlane_b32 s56, v134
	v_readfirstlane_b32 s57, v135
	v_add_u32_e32 v136, 0xc000, v234
	v_add_u32_e32 v137, 0xe000, v234
	ds_read_b128 v[138:141], v206
	ds_read_b128 v[142:145], v206 offset:1024
	ds_read_b128 v[146:149], v206 offset:2048
	ds_read_b128 v[150:153], v206 offset:3072
	s_add_u32 vcc_lo, s8, s80
	s_addc_u32 vcc_hi, s9, s81
	ds_read_b128 v[154:157], v241
	ds_read_b128 v[158:161], v241 offset:1024
	ds_read_b128 v[162:165], v241 offset:2048
	ds_read_b128 v[166:169], v241 offset:3072
	ds_read_b128 v[170:173], v241 offset:4096
	ds_read_b128 v[174:177], v241 offset:5120
	ds_read_b128 v[178:181], v241 offset:6144
	ds_read_b128 v[182:185], v241 offset:7168
	s_mov_b32 m0, s16
	s_add_u32 s98, vcc_lo, s12
	s_addc_u32 s99, vcc_hi, s13
	global_load_lds_dwordx4 v221, s[98:99]
	s_mov_b32 m0, s32
	s_add_u32 s98, vcc_lo, s36
	s_addc_u32 s99, vcc_hi, s37
	global_load_lds_dwordx4 v221, s[98:99]
	s_waitcnt lgkmcnt(8)
	s_waitcnt vmcnt(10)
	s_barrier
	s_waitcnt lgkmcnt(0)
	s_waitcnt lgkmcnt(0)
	v_mfma_f32_16x16x32_bf16 v[126:129], v[138:141], v[154:157], 0
	v_mfma_f32_16x16x32_bf16 v[122:125], v[146:149], v[154:157], 0
	v_mfma_f32_16x16x32_bf16 v[118:121], v[138:141], v[162:165], 0
	v_mfma_f32_16x16x32_bf16 v[114:117], v[146:149], v[162:165], 0
	v_mfma_f32_16x16x32_bf16 v[110:113], v[138:141], v[170:173], 0
	v_mfma_f32_16x16x32_bf16 v[106:109], v[146:149], v[170:173], 0
	v_mfma_f32_16x16x32_bf16 v[102:105], v[138:141], v[178:181], 0
	v_mfma_f32_16x16x32_bf16 v[98:101], v[146:149], v[178:181], 0
	v_mfma_f32_16x16x32_bf16 v[126:129], v[142:145], v[158:161], v[126:129]
	v_mfma_f32_16x16x32_bf16 v[122:125], v[150:153], v[158:161], v[122:125]
	v_mfma_f32_16x16x32_bf16 v[118:121], v[142:145], v[166:169], v[118:121]
	v_mfma_f32_16x16x32_bf16 v[114:117], v[150:153], v[166:169], v[114:117]
	v_mfma_f32_16x16x32_bf16 v[110:113], v[142:145], v[174:177], v[110:113]
	v_mfma_f32_16x16x32_bf16 v[106:109], v[150:153], v[174:177], v[106:109]
	v_mfma_f32_16x16x32_bf16 v[102:105], v[142:145], v[182:185], v[102:105]
	v_mfma_f32_16x16x32_bf16 v[98:101], v[150:153], v[182:185], v[98:101]
	s_barrier
	s_add_u32 s0, s6, s80
	ds_read_b128 v[186:189], v207
	ds_read_b128 v[190:193], v207 offset:1024
	ds_read_b128 v[194:197], v207 offset:2048
	ds_read_b128 v[198:201], v207 offset:3072
	s_addc_u32 s1, s7, s81
	s_mov_b32 m0, s44
	s_add_u32 s98, s0, s34
	s_addc_u32 s99, s1, s35
	global_load_lds_dwordx4 v221, s[98:99]
	s_mov_b32 m0, s45
	s_add_u32 s98, s0, s64
	s_addc_u32 s99, s1, s65
	global_load_lds_dwordx4 v221, s[98:99]
	s_waitcnt vmcnt(10)
	s_barrier
; #define LDA(dst, b, h) for (int m = 0; m < 4; ++m) for (int k = 0; k < 2; ++k) \
;     dst[m][k] = *reinterpret_cast<const bf16x8*>((char*)SA(b, h) + a_thr + (m * 2 + k) * 1024)
; #define LDB(dst, b, h) for (int n = 0; n < 2; ++n) for (int k = 0; k < 2; ++k) \
;     dst[n][k] = *reinterpret_cast<const bf16x8*>((char*)SB(b, h) + b_thr + (n * 2 + k) * 1024)
; #define MMA(ai, bj, At, Btf) do { __builtin_amdgcn_s_setprio(1); \
;     for (int m = 0; m < 4; ++m) for (int n = 0; n < 2; ++n) for (int k = 0; k < 2; ++k) \
;       acc[ai][bj][m][n] = __builtin_amdgcn_mfma_f32_16x16x32_bf16(Btf[n][k], At[m][k], acc[ai][bj][m][n], 0, 0, 0); \
;     __builtin_amdgcn_s_setprio(0); } while (0)
; #define WAIT_V(n) asm volatile("s_waitcnt vmcnt(" #n ")" ::: "memory")
; #define WAIT_L(n) asm volatile("s_waitcnt lgkmcnt(" #n ")" ::: "memory")
; #define BAR __builtin_amdgcn_s_barrier()
; #define SCHED __builtin_amdgcn_sched_barrier(0)
; template <bool OVL, bool PANEL = false, class Epi>
; __device__ __forceinline__ void gemm_phase(const bf16_t* __restrict__ A, long lda, const bf16_t* __restrict__ Bt, long ldb, int nM, int nN, int K,
;                                            const Epi& epi, bf16_t* shm, int w0) {
;     ...
;       BAR; WAIT_L(0); MMA(0, 1, At, B1); BAR;
;       LDA(At, 0, 1); STAGE(SA(0, 0), A, lda, aoff, brow, t + 2);
;       BAR; WAIT_L(0); MMA(1, 0, At, B0); BAR; SCHED;
;       STAGE(SB(0, 1), Bt, ldb, boff, bcol + HALF, t + 2);
;       WAIT_V(6); BAR; MMA(1, 1, At, B1); BAR;
;       LDB(B0, 1, 0); SCHED; LDA(At, 1, 0); STAGE(SA(0, 1), A, lda, aoff, brow + HALF, t + 2);
;       WAIT_L(8); BAR; WAIT_L(0); MMA(0, 0, At, B0); BAR; SCHED;
	s_waitcnt lgkmcnt(0)
	s_waitcnt lgkmcnt(0)
	v_mfma_f32_16x16x32_bf16 v[94:97], v[186:189], v[154:157], 0
	v_mfma_f32_16x16x32_bf16 v[90:93], v[194:197], v[154:157], 0
	v_mfma_f32_16x16x32_bf16 v[86:89], v[186:189], v[162:165], 0
	v_mfma_f32_16x16x32_bf16 v[82:85], v[194:197], v[162:165], 0
	v_mfma_f32_16x16x32_bf16 v[78:81], v[186:189], v[170:173], 0
	v_mfma_f32_16x16x32_bf16 v[74:77], v[194:197], v[170:173], 0
	v_mfma_f32_16x16x32_bf16 v[70:73], v[186:189], v[178:181], 0
	v_mfma_f32_16x16x32_bf16 v[66:69], v[194:197], v[178:181], 0
	v_mfma_f32_16x16x32_bf16 v[94:97], v[190:193], v[158:161], v[94:97]
	v_mfma_f32_16x16x32_bf16 v[90:93], v[198:201], v[158:161], v[90:93]
	v_mfma_f32_16x16x32_bf16 v[86:89], v[190:193], v[166:169], v[86:89]
	v_mfma_f32_16x16x32_bf16 v[82:85], v[198:201], v[166:169], v[82:85]
	v_mfma_f32_16x16x32_bf16 v[78:81], v[190:193], v[174:177], v[78:81]
	v_mfma_f32_16x16x32_bf16 v[74:77], v[198:201], v[174:177], v[74:77]
	v_mfma_f32_16x16x32_bf16 v[70:73], v[190:193], v[182:185], v[70:73]
	v_mfma_f32_16x16x32_bf16 v[66:69], v[198:201], v[182:185], v[66:69]
	s_barrier
	ds_read_b128 v[154:157], v241 offset:16384
	ds_read_b128 v[158:161], v241 offset:17408
	ds_read_b128 v[162:165], v241 offset:18432
	ds_read_b128 v[166:169], v241 offset:19456
	ds_read_b128 v[170:173], v241 offset:20480
	ds_read_b128 v[174:177], v241 offset:21504
	ds_read_b128 v[178:181], v241 offset:22528
	ds_read_b128 v[182:185], v241 offset:23552
	s_mov_b32 m0, s46
	s_add_u32 s98, vcc_lo, s34
	s_addc_u32 s99, vcc_hi, s35
	global_load_lds_dwordx4 v221, s[98:99]
	s_mov_b32 m0, s47
	s_add_u32 s98, vcc_lo, s64
	s_addc_u32 s99, vcc_hi, s65
	global_load_lds_dwordx4 v221, s[98:99]
	s_barrier
	s_waitcnt lgkmcnt(0)
	s_waitcnt lgkmcnt(0)
	v_mfma_f32_16x16x32_bf16 v[62:65], v[138:141], v[154:157], 0
	v_mfma_f32_16x16x32_bf16 v[58:61], v[146:149], v[154:157], 0
	v_mfma_f32_16x16x32_bf16 v[54:57], v[138:141], v[162:165], 0
	v_mfma_f32_16x16x32_bf16 v[50:53], v[146:149], v[162:165], 0
	v_mfma_f32_16x16x32_bf16 v[46:49], v[138:141], v[170:173], 0
	v_mfma_f32_16x16x32_bf16 v[42:45], v[146:149], v[170:173], 0
	v_mfma_f32_16x16x32_bf16 v[38:41], v[138:141], v[178:181], 0
	v_mfma_f32_16x16x32_bf16 v[34:37], v[146:149], v[178:181], 0
	v_mfma_f32_16x16x32_bf16 v[62:65], v[142:145], v[158:161], v[62:65]
	v_mfma_f32_16x16x32_bf16 v[58:61], v[150:153], v[158:161], v[58:61]
	v_mfma_f32_16x16x32_bf16 v[54:57], v[142:145], v[166:169], v[54:57]
	v_mfma_f32_16x16x32_bf16 v[50:53], v[150:153], v[166:169], v[50:53]
	v_mfma_f32_16x16x32_bf16 v[46:49], v[142:145], v[174:177], v[46:49]
	v_mfma_f32_16x16x32_bf16 v[42:45], v[150:153], v[174:177], v[42:45]
	v_mfma_f32_16x16x32_bf16 v[38:41], v[142:145], v[182:185], v[38:41]
	v_mfma_f32_16x16x32_bf16 v[34:37], v[150:153], v[182:185], v[34:37]
	s_barrier
	s_mov_b32 m0, s48
	s_add_u32 s98, s0, s68
	s_addc_u32 s99, s1, s69
	global_load_lds_dwordx4 v221, s[98:99]
	s_mov_b32 m0, s49
	s_add_u32 s98, s0, s70
	s_addc_u32 s99, s1, s71
	global_load_lds_dwordx4 v221, s[98:99]
	s_waitcnt vmcnt(10)
	s_barrier
	v_mfma_f32_16x16x32_bf16 v[30:33], v[186:189], v[154:157], 0
	v_mfma_f32_16x16x32_bf16 v[26:29], v[194:197], v[154:157], 0
	v_mfma_f32_16x16x32_bf16 v[22:25], v[186:189], v[162:165], 0
	v_mfma_f32_16x16x32_bf16 v[18:21], v[194:197], v[162:165], 0
	v_mfma_f32_16x16x32_bf16 v[14:17], v[186:189], v[170:173], 0
	v_mfma_f32_16x16x32_bf16 v[10:13], v[194:197], v[170:173], 0
	v_mfma_f32_16x16x32_bf16 v[6:9], v[186:189], v[178:181], 0
	v_mfma_f32_16x16x32_bf16 v[2:5], v[194:197], v[178:181], 0
	v_mfma_f32_16x16x32_bf16 v[30:33], v[190:193], v[158:161], v[30:33]
	v_mfma_f32_16x16x32_bf16 v[26:29], v[198:201], v[158:161], v[26:29]
	v_mfma_f32_16x16x32_bf16 v[22:25], v[190:193], v[166:169], v[22:25]
	v_mfma_f32_16x16x32_bf16 v[18:21], v[198:201], v[166:169], v[18:21]
	v_mfma_f32_16x16x32_bf16 v[14:17], v[190:193], v[174:177], v[14:17]
	v_mfma_f32_16x16x32_bf16 v[10:13], v[198:201], v[174:177], v[10:13]
	v_mfma_f32_16x16x32_bf16 v[6:9], v[190:193], v[182:185], v[6:9]
	v_mfma_f32_16x16x32_bf16 v[2:5], v[198:201], v[182:185], v[2:5]
	s_barrier
	ds_read_b128 v[138:141], v208
	ds_read_b128 v[142:145], v208 offset:1024
	ds_read_b128 v[146:149], v208 offset:2048
	ds_read_b128 v[150:153], v208 offset:3072
	ds_read_b128 v[154:157], v241 offset:32768
	ds_read_b128 v[158:161], v241 offset:33792
	ds_read_b128 v[162:165], v241 offset:34816
	ds_read_b128 v[166:169], v241 offset:35840
	ds_read_b128 v[170:173], v241 offset:36864
	ds_read_b128 v[174:177], v241 offset:37888
	ds_read_b128 v[178:181], v241 offset:38912
	ds_read_b128 v[182:185], v241 offset:39936
	s_mov_b32 m0, s50
	s_add_u32 s98, vcc_lo, s68
	s_addc_u32 s99, vcc_hi, s69
	global_load_lds_dwordx4 v221, s[98:99]
	s_mov_b32 m0, s51
	s_add_u32 s98, vcc_lo, s70
	s_addc_u32 s99, vcc_hi, s71
	global_load_lds_dwordx4 v221, s[98:99]
	s_waitcnt lgkmcnt(8)
	s_waitcnt vmcnt(10)
	s_barrier
; #define LDA(dst, b, h) for (int m = 0; m < 4; ++m) for (int k = 0; k < 2; ++k) \
;     dst[m][k] = *reinterpret_cast<const bf16x8*>((char*)SA(b, h) + a_thr + (m * 2 + k) * 1024)
; #define LDB(dst, b, h) for (int n = 0; n < 2; ++n) for (int k = 0; k < 2; ++k) \
;     dst[n][k] = *reinterpret_cast<const bf16x8*>((char*)SB(b, h) + b_thr + (n * 2 + k) * 1024)
; #define MMA(ai, bj, At, Btf) do { __builtin_amdgcn_s_setprio(1); \
;     for (int m = 0; m < 4; ++m) for (int n = 0; n < 2; ++n) for (int k = 0; k < 2; ++k) \
;       acc[ai][bj][m][n] = __builtin_amdgcn_mfma_f32_16x16x32_bf16(Btf[n][k], At[m][k], acc[ai][bj][m][n], 0, 0, 0); \
;     __builtin_amdgcn_s_setprio(0); } while (0)
; #define WAIT_V(n) asm volatile("s_waitcnt vmcnt(" #n ")" ::: "memory")
; #define WAIT_L(n) asm volatile("s_waitcnt lgkmcnt(" #n ")" ::: "memory")
; #define BAR __builtin_amdgcn_s_barrier()
; #define SCHED __builtin_amdgcn_sched_barrier(0)
; template <bool OVL, bool PANEL = false, class Epi>
; __device__ __forceinline__ void gemm_phase(const bf16_t* __restrict__ A, long lda, const bf16_t* __restrict__ Bt, long ldb, int nM, int nN, int K,
;                                            const Epi& epi, bf16_t* shm, int w0) {
;     ...
;       WAIT_L(8); BAR; WAIT_L(0); MMA(0, 0, At, B0); BAR; SCHED;
;       LDB(B1, 1, 1); STAGE(SB(1, 0), Bt, ldb, boff, bcol, t + 3);
;       BAR; WAIT_L(0); MMA(0, 1, At, B1); BAR;
;       LDA(At, 1, 1); STAGE(SA(1, 0), A, lda, aoff, brow, t + 3);
;       BAR; WAIT_L(0); MMA(1, 0, At, B0); BAR; SCHED;
;       STAGE(SB(1, 1), Bt, ldb, boff, bcol + HALF, t + 3);
;       WAIT_V(6); BAR; MMA(1, 1, At, B1); BAR;
	s_waitcnt lgkmcnt(0)
	s_waitcnt lgkmcnt(0)
	v_mfma_f32_16x16x32_bf16 v[126:129], v[138:141], v[154:157], v[126:129]
	v_mfma_f32_16x16x32_bf16 v[122:125], v[146:149], v[154:157], v[122:125]
	v_mfma_f32_16x16x32_bf16 v[118:121], v[138:141], v[162:165], v[118:121]
	v_mfma_f32_16x16x32_bf16 v[114:117], v[146:149], v[162:165], v[114:117]
	v_mfma_f32_16x16x32_bf16 v[110:113], v[138:141], v[170:173], v[110:113]
	v_mfma_f32_16x16x32_bf16 v[106:109], v[146:149], v[170:173], v[106:109]
	v_mfma_f32_16x16x32_bf16 v[102:105], v[138:141], v[178:181], v[102:105]
	v_mfma_f32_16x16x32_bf16 v[98:101], v[146:149], v[178:181], v[98:101]
	v_mfma_f32_16x16x32_bf16 v[126:129], v[142:145], v[158:161], v[126:129]
	v_mfma_f32_16x16x32_bf16 v[122:125], v[150:153], v[158:161], v[122:125]
	v_mfma_f32_16x16x32_bf16 v[118:121], v[142:145], v[166:169], v[118:121]
	v_mfma_f32_16x16x32_bf16 v[114:117], v[150:153], v[166:169], v[114:117]
	v_mfma_f32_16x16x32_bf16 v[110:113], v[142:145], v[174:177], v[110:113]
	v_mfma_f32_16x16x32_bf16 v[106:109], v[150:153], v[174:177], v[106:109]
	v_mfma_f32_16x16x32_bf16 v[102:105], v[142:145], v[182:185], v[102:105]
	v_mfma_f32_16x16x32_bf16 v[98:101], v[150:153], v[182:185], v[98:101]
	s_barrier
	ds_read_b128 v[186:189], v209
	ds_read_b128 v[190:193], v209 offset:1024
	ds_read_b128 v[194:197], v209 offset:2048
	ds_read_b128 v[198:201], v209 offset:3072
	s_mov_b32 m0, s52
	s_add_u32 s98, s0, s94
	s_addc_u32 s99, s1, s95
	global_load_lds_dwordx4 v221, s[98:99]
	s_mov_b32 m0, s53
	s_add_u32 s98, s0, s72
	s_addc_u32 s99, s1, s73
	global_load_lds_dwordx4 v221, s[98:99]
	s_waitcnt vmcnt(10)
	s_barrier
	s_waitcnt lgkmcnt(0)
	s_waitcnt lgkmcnt(0)
	v_mfma_f32_16x16x32_bf16 v[94:97], v[186:189], v[154:157], v[94:97]
	v_mfma_f32_16x16x32_bf16 v[90:93], v[194:197], v[154:157], v[90:93]
	v_mfma_f32_16x16x32_bf16 v[86:89], v[186:189], v[162:165], v[86:89]
	v_mfma_f32_16x16x32_bf16 v[82:85], v[194:197], v[162:165], v[82:85]
	v_mfma_f32_16x16x32_bf16 v[78:81], v[186:189], v[170:173], v[78:81]
	v_mfma_f32_16x16x32_bf16 v[74:77], v[194:197], v[170:173], v[74:77]
	v_mfma_f32_16x16x32_bf16 v[70:73], v[186:189], v[178:181], v[70:73]
	v_mfma_f32_16x16x32_bf16 v[66:69], v[194:197], v[178:181], v[66:69]
	v_mfma_f32_16x16x32_bf16 v[94:97], v[190:193], v[158:161], v[94:97]
	v_mfma_f32_16x16x32_bf16 v[90:93], v[198:201], v[158:161], v[90:93]
	v_mfma_f32_16x16x32_bf16 v[86:89], v[190:193], v[166:169], v[86:89]
	v_mfma_f32_16x16x32_bf16 v[82:85], v[198:201], v[166:169], v[82:85]
	v_mfma_f32_16x16x32_bf16 v[78:81], v[190:193], v[174:177], v[78:81]
	v_mfma_f32_16x16x32_bf16 v[74:77], v[198:201], v[174:177], v[74:77]
	v_mfma_f32_16x16x32_bf16 v[70:73], v[190:193], v[182:185], v[70:73]
	v_mfma_f32_16x16x32_bf16 v[66:69], v[198:201], v[182:185], v[66:69]
	s_barrier
	ds_read_b128 v[154:157], v241 offset:49152
	ds_read_b128 v[158:161], v241 offset:50176
	ds_read_b128 v[162:165], v241 offset:51200
	ds_read_b128 v[166:169], v241 offset:52224
	ds_read_b128 v[170:173], v241 offset:53248
	ds_read_b128 v[174:177], v241 offset:54272
	ds_read_b128 v[178:181], v241 offset:55296
	ds_read_b128 v[182:185], v241 offset:56320
	s_mov_b32 m0, s54
	s_add_u32 s98, vcc_lo, s94
	s_addc_u32 s99, vcc_hi, s95
	global_load_lds_dwordx4 v221, s[98:99]
	s_mov_b32 m0, s55
	s_add_u32 s98, vcc_lo, s72
	s_addc_u32 s99, vcc_hi, s73
	global_load_lds_dwordx4 v221, s[98:99]
	s_barrier
	s_waitcnt lgkmcnt(0)
	s_waitcnt lgkmcnt(0)
	v_mfma_f32_16x16x32_bf16 v[62:65], v[138:141], v[154:157], v[62:65]
	v_mfma_f32_16x16x32_bf16 v[58:61], v[146:149], v[154:157], v[58:61]
	v_mfma_f32_16x16x32_bf16 v[54:57], v[138:141], v[162:165], v[54:57]
	v_mfma_f32_16x16x32_bf16 v[50:53], v[146:149], v[162:165], v[50:53]
	v_mfma_f32_16x16x32_bf16 v[46:49], v[138:141], v[170:173], v[46:49]
	v_mfma_f32_16x16x32_bf16 v[42:45], v[146:149], v[170:173], v[42:45]
	v_mfma_f32_16x16x32_bf16 v[38:41], v[138:141], v[178:181], v[38:41]
	v_mfma_f32_16x16x32_bf16 v[34:37], v[146:149], v[178:181], v[34:37]
	v_mfma_f32_16x16x32_bf16 v[62:65], v[142:145], v[158:161], v[62:65]
	v_mfma_f32_16x16x32_bf16 v[58:61], v[150:153], v[158:161], v[58:61]
	v_mfma_f32_16x16x32_bf16 v[54:57], v[142:145], v[166:169], v[54:57]
	v_mfma_f32_16x16x32_bf16 v[50:53], v[150:153], v[166:169], v[50:53]
	v_mfma_f32_16x16x32_bf16 v[46:49], v[142:145], v[174:177], v[46:49]
	v_mfma_f32_16x16x32_bf16 v[42:45], v[150:153], v[174:177], v[42:45]
	v_mfma_f32_16x16x32_bf16 v[38:41], v[142:145], v[182:185], v[38:41]
	v_mfma_f32_16x16x32_bf16 v[34:37], v[150:153], v[182:185], v[34:37]
	s_barrier
	s_mov_b32 m0, s56
	s_add_u32 s98, s0, s14
	s_addc_u32 s99, s1, s15
	global_load_lds_dwordx4 v221, s[98:99]
	s_mov_b32 m0, s57
	s_add_u32 s98, s0, s18
	s_addc_u32 s99, s1, s19
	global_load_lds_dwordx4 v221, s[98:99]
	s_add_i32 s2, s2, 2
	s_add_u32 s80, s80, 0x100
	s_addc_u32 s81, s81, 0
	s_cmp_gt_u32 s2, 11
	s_waitcnt vmcnt(10)
	s_barrier
	v_mfma_f32_16x16x32_bf16 v[30:33], v[186:189], v[154:157], v[30:33]
	v_mfma_f32_16x16x32_bf16 v[26:29], v[194:197], v[154:157], v[26:29]
	v_mfma_f32_16x16x32_bf16 v[22:25], v[186:189], v[162:165], v[22:25]
	v_mfma_f32_16x16x32_bf16 v[18:21], v[194:197], v[162:165], v[18:21]
	v_mfma_f32_16x16x32_bf16 v[14:17], v[186:189], v[170:173], v[14:17]
	v_mfma_f32_16x16x32_bf16 v[10:13], v[194:197], v[170:173], v[10:13]
	v_mfma_f32_16x16x32_bf16 v[6:9], v[186:189], v[178:181], v[6:9]
	v_mfma_f32_16x16x32_bf16 v[2:5], v[194:197], v[178:181], v[2:5]
	v_mfma_f32_16x16x32_bf16 v[30:33], v[190:193], v[158:161], v[30:33]
	v_mfma_f32_16x16x32_bf16 v[26:29], v[198:201], v[158:161], v[26:29]
	v_mfma_f32_16x16x32_bf16 v[22:25], v[190:193], v[166:169], v[22:25]
	v_mfma_f32_16x16x32_bf16 v[18:21], v[198:201], v[166:169], v[18:21]
	v_mfma_f32_16x16x32_bf16 v[14:17], v[190:193], v[174:177], v[14:17]
	v_mfma_f32_16x16x32_bf16 v[10:13], v[198:201], v[174:177], v[10:13]
	v_mfma_f32_16x16x32_bf16 v[6:9], v[190:193], v[182:185], v[6:9]
	v_mfma_f32_16x16x32_bf16 v[2:5], v[198:201], v[182:185], v[2:5]
	s_barrier

; #define LDA(dst, b, h) for (int m = 0; m < 4; ++m) for (int k = 0; k < 2; ++k) \
;     dst[m][k] = *reinterpret_cast<const bf16x8*>((char*)SA(b, h) + a_thr + (m * 2 + k) * 1024)
; #define LDB(dst, b, h) for (int n = 0; n < 2; ++n) for (int k = 0; k < 2; ++k) \
;     dst[n][k] = *reinterpret_cast<const bf16x8*>((char*)SB(b, h) + b_thr + (n * 2 + k) * 1024)
; #define MMA(ai, bj, At, Btf) do { __builtin_amdgcn_s_setprio(1); \
;     for (int m = 0; m < 4; ++m) for (int n = 0; n < 2; ++n) for (int k = 0; k < 2; ++k) \
;       acc[ai][bj][m][n] = __builtin_amdgcn_mfma_f32_16x16x32_bf16(Btf[n][k], At[m][k], acc[ai][bj][m][n], 0, 0, 0); \
;     __builtin_amdgcn_s_setprio(0); } while (0)
; #define WAIT_V(n) asm volatile("s_waitcnt vmcnt(" #n ")" ::: "memory")
; #define WAIT_L(n) asm volatile("s_waitcnt lgkmcnt(" #n ")" ::: "memory")
; #define BAR __builtin_amdgcn_s_barrier()
; #define SCHED __builtin_amdgcn_sched_barrier(0)
; template <bool OVL, bool PANEL = false, class Epi>
; __device__ __forceinline__ void gemm_phase(const bf16_t* __restrict__ A, long lda, const bf16_t* __restrict__ Bt, long ldb, int nM, int nN, int K,
;                                            const Epi& epi, bf16_t* shm, int w0) {
;     ...
;   for (int it = 0; have; ++it) {
;     const int brow = pm * BM, bcol = pn * BM;
;     f32x4 acc[2][2][4][2];
; #pragma unroll
;     for (int a0 = 0; a0 < 2; ++a0)
; #pragma unroll
;       for (int a1 = 0; a1 < 2; ++a1)
; #pragma unroll
;         for (int a2 = 0; a2 < 4; ++a2)
; #pragma unroll
;           for (int a3 = 0; a3 < 2; ++a3) acc[a0][a1][a2][a3] = (f32x4){0.f, 0.f, 0.f, 0.f};
;     bf16x8 At[4][2], B0[2][2], B1[2][2];
;     if (wr == 1) BAR;
;     WAIT_V(4); BAR;
;     STAGE(SB(1, 0), Bt, ldb, boff, bcol, 1); STAGE(SA(1, 0), A, lda, aoff, brow, 1); STAGE(SB(1, 1), Bt, ldb, boff, bcol + HALF, 1);
;     WAIT_V(6); BAR;
;     for (int t = 0; t < nt - 2; t += 2) {
;       LDB(B0, 0, 0); SCHED; LDA(At, 0, 0); STAGE(SA(1, 1), A, lda, aoff, brow + HALF, t + 1);
;       WAIT_L(8); BAR; WAIT_L(0); MMA(0, 0, At, B0); BAR; SCHED;
;       LDB(B1, 0, 1); STAGE(SB(0, 0), Bt, ldb, boff, bcol, t + 2);
.LBB0_1052:
	s_or_b64 exec, exec, s[0:1]
	s_lshl_b32 s12, s57, 8
	s_ashr_i32 s13, s12, 31
	v_readlane_b32 s16, v252, 3
	s_lshl_b32 s0, s58, 8
	s_lshl_b64 s[8:9], s[12:13], 11
	v_readlane_b32 s22, v252, 9
	v_readlane_b32 s23, v252, 10
	s_add_u32 s8, s22, s8
	v_readlane_b32 s17, v252, 4
	s_addc_u32 s9, s23, s9
	v_mov_b32_e32 v0, v135
	v_add_u32_e32 v130, s96, v134
	s_waitcnt vmcnt(4)
	s_barrier
	s_mov_b64 s[16:17], 0x80
	v_lshl_add_u64 v[2:3], s[8:9], 0, v[0:1]
	v_readfirstlane_b32 s1, v130
	v_add_u32_e32 v131, 0x2000, v130
	v_lshl_add_u64 v[4:5], v[2:3], 0, s[16:17]
	s_mov_b32 m0, s1
	v_readfirstlane_b32 s1, v131
	global_load_lds_dwordx4 v[4:5], off
	s_mov_b32 m0, s1
	s_ashr_i32 s1, s0, 31
	v_readlane_b32 s40, v252, 20
	s_lshl_b64 s[10:11], s[0:1], 11
	v_readlane_b32 s46, v252, 26
	v_readlane_b32 s18, v252, 5
	v_readlane_b32 s19, v252, 6
	v_readlane_b32 s47, v252, 27
	s_add_u32 s10, s46, s10
	s_mov_b64 s[18:19], 0x20080
	s_addc_u32 s11, s47, s11
	s_or_b32 s14, s12, 0x80
	v_lshl_add_u64 v[2:3], v[2:3], 0, s[18:19]
	v_mov_b32_e32 v0, v135
	v_add_u32_e32 v132, 0x8000, v138
	s_ashr_i32 s15, s14, 31
	global_load_lds_dwordx4 v[2:3], off
	v_readfirstlane_b32 s1, v132
	v_lshl_add_u64 v[2:3], s[10:11], 0, v[0:1]
	v_add_u32_e32 v133, 0xa000, v138
	s_lshl_b64 s[14:15], s[14:15], 11
	v_lshl_add_u64 v[4:5], v[2:3], 0, s[16:17]
	s_mov_b32 m0, s1
	v_readfirstlane_b32 s1, v133
	s_add_u32 s14, s22, s14
	global_load_lds_dwordx4 v[4:5], off
	v_lshl_add_u64 v[2:3], v[2:3], 0, s[18:19]
	s_mov_b32 m0, s1
	s_addc_u32 s15, s23, s15
	v_mov_b32_e32 v0, v135
	v_add_u32_e32 v148, s75, v134
	global_load_lds_dwordx4 v[2:3], off
	v_readfirstlane_b32 s1, v148
	v_lshl_add_u64 v[2:3], s[14:15], 0, v[0:1]
	v_add_u32_e32 v149, 0x2000, v148
	v_lshl_add_u64 v[4:5], v[2:3], 0, s[16:17]
	s_mov_b32 m0, s1
	v_readfirstlane_b32 s1, v149
	global_load_lds_dwordx4 v[4:5], off
	v_lshl_add_u64 v[2:3], v[2:3], 0, s[18:19]
	s_mov_b32 m0, s1
	v_readlane_b32 s20, v252, 7
	global_load_lds_dwordx4 v[2:3], off
	s_waitcnt vmcnt(6)
	v_readlane_b32 s21, v252, 8
	s_mov_b32 s1, -2
	s_mov_b64 s[14:15], 0
	s_waitcnt lgkmcnt(0)
	s_mov_b64 s[16:17], 0x40080
	s_mov_b64 s[18:19], 0x40180
	s_mov_b64 s[20:21], 0x60180
	v_readlane_b32 s24, v252, 11
	v_readlane_b32 s25, v252, 12
	v_readlane_b32 s26, v252, 13
	v_readlane_b32 s27, v252, 14
	v_readlane_b32 s28, v252, 15
	v_readlane_b32 s29, v252, 16
	v_readlane_b32 s30, v252, 17
	v_readlane_b32 s31, v252, 18
	v_readlane_b32 s41, v252, 21
	v_readlane_b32 s42, v252, 22
	v_readlane_b32 s43, v252, 23
	v_readlane_b32 s44, v252, 24
	v_readlane_b32 s45, v252, 25
	v_readlane_b32 s48, v252, 28
	v_readlane_b32 s49, v252, 29
	v_readlane_b32 s50, v252, 30
	v_readlane_b32 s51, v252, 31
	v_readlane_b32 s52, v252, 32
	v_readlane_b32 s53, v252, 33
	v_readlane_b32 s54, v252, 34
	v_readlane_b32 s55, v252, 35
	s_barrier
	v_add_u32_e32 v184, s2, v144
	v_readfirstlane_b32 s22, v138
	s_add_u32 s22, s22, 0xc000
	v_readfirstlane_b32 s23, v138
	s_add_u32 s23, s23, 0xe000
	v_add_u32_e32 v185, s33, v144
	v_readfirstlane_b32 s24, v136
	v_readfirstlane_b32 s25, v137
	v_readfirstlane_b32 s26, v138
	v_readfirstlane_b32 s27, v139
	v_readfirstlane_b32 s28, v140
	v_readfirstlane_b32 s29, v141
	v_add_u32_e32 v186, s96, v144
	v_readfirstlane_b32 s30, v142
	v_readfirstlane_b32 s31, v143
	v_add_u32_e32 v187, s75, v144
	v_readfirstlane_b32 s32, v130
	v_readfirstlane_b32 s44, v131
	v_readfirstlane_b32 s45, v132
	v_readfirstlane_b32 s46, v133
	v_readfirstlane_b32 s47, v148
	v_readfirstlane_b32 s48, v149
	v_add_u32_e32 v150, 0xc000, v138
	v_add_u32_e32 v151, 0xe000, v138
	ds_read_b128 v[152:155], v184
	ds_read_b128 v[156:159], v184 offset:1024
	ds_read_b128 v[160:163], v184 offset:2048
	ds_read_b128 v[164:167], v184 offset:3072
	s_add_u32 s40, s10, s14
	s_addc_u32 s41, s11, s15
	ds_read_b128 v[168:171], v147
	ds_read_b128 v[172:175], v147 offset:1024
	ds_read_b128 v[176:179], v147 offset:2048
	ds_read_b128 v[194:197], v147 offset:3072
	ds_read_b128 v[198:201], v147 offset:4096
	ds_read_b128 v[202:205], v147 offset:5120
	ds_read_b128 v[206:209], v147 offset:6144
	ds_read_b128 v[210:213], v147 offset:7168
	s_mov_b32 m0, s22
	s_add_u32 s98, s40, s16
	s_addc_u32 s99, s41, s17
	global_load_lds_dwordx4 v135, s[98:99]
	s_mov_b32 m0, s23
	s_add_u32 s98, s40, s36
	s_addc_u32 s99, s41, s37
	global_load_lds_dwordx4 v135, s[98:99]
	s_waitcnt lgkmcnt(8)
	s_waitcnt vmcnt(10)
	s_barrier
	s_waitcnt lgkmcnt(0)
	s_waitcnt lgkmcnt(0)
	v_mfma_f32_16x16x32_bf16 v[126:129], v[152:155], v[168:171], 0
	v_mfma_f32_16x16x32_bf16 v[122:125], v[160:163], v[168:171], 0
	v_mfma_f32_16x16x32_bf16 v[118:121], v[152:155], v[176:179], 0
	v_mfma_f32_16x16x32_bf16 v[114:117], v[160:163], v[176:179], 0
	v_mfma_f32_16x16x32_bf16 v[110:113], v[152:155], v[198:201], 0
	v_mfma_f32_16x16x32_bf16 v[106:109], v[160:163], v[198:201], 0
	v_mfma_f32_16x16x32_bf16 v[102:105], v[152:155], v[206:209], 0
	v_mfma_f32_16x16x32_bf16 v[98:101], v[160:163], v[206:209], 0
	v_mfma_f32_16x16x32_bf16 v[126:129], v[156:159], v[172:175], v[126:129]
	v_mfma_f32_16x16x32_bf16 v[122:125], v[164:167], v[172:175], v[122:125]
	v_mfma_f32_16x16x32_bf16 v[118:121], v[156:159], v[194:197], v[118:121]
	v_mfma_f32_16x16x32_bf16 v[114:117], v[164:167], v[194:197], v[114:117]
	v_mfma_f32_16x16x32_bf16 v[110:113], v[156:159], v[202:205], v[110:113]
	v_mfma_f32_16x16x32_bf16 v[106:109], v[164:167], v[202:205], v[106:109]
	v_mfma_f32_16x16x32_bf16 v[102:105], v[156:159], v[210:213], v[102:105]
	v_mfma_f32_16x16x32_bf16 v[98:101], v[164:167], v[210:213], v[98:101]
	s_barrier
; #define LDA(dst, b, h) for (int m = 0; m < 4; ++m) for (int k = 0; k < 2; ++k) \
;     dst[m][k] = *reinterpret_cast<const bf16x8*>((char*)SA(b, h) + a_thr + (m * 2 + k) * 1024)
; #define LDB(dst, b, h) for (int n = 0; n < 2; ++n) for (int k = 0; k < 2; ++k) \
;     dst[n][k] = *reinterpret_cast<const bf16x8*>((char*)SB(b, h) + b_thr + (n * 2 + k) * 1024)
; #define MMA(ai, bj, At, Btf) do { __builtin_amdgcn_s_setprio(1); \
;     for (int m = 0; m < 4; ++m) for (int n = 0; n < 2; ++n) for (int k = 0; k < 2; ++k) \
;       acc[ai][bj][m][n] = __builtin_amdgcn_mfma_f32_16x16x32_bf16(Btf[n][k], At[m][k], acc[ai][bj][m][n], 0, 0, 0); \
;     __builtin_amdgcn_s_setprio(0); } while (0)
; #define WAIT_V(n) asm volatile("s_waitcnt vmcnt(" #n ")" ::: "memory")
; #define WAIT_L(n) asm volatile("s_waitcnt lgkmcnt(" #n ")" ::: "memory")
; #define BAR __builtin_amdgcn_s_barrier()
; #define SCHED __builtin_amdgcn_sched_barrier(0)
; template <bool OVL, bool PANEL = false, class Epi>
; __device__ __forceinline__ void gemm_phase(const bf16_t* __restrict__ A, long lda, const bf16_t* __restrict__ Bt, long ldb, int nM, int nN, int K,
;                                            const Epi& epi, bf16_t* shm, int w0) {
;     ...
;       LDB(B1, 0, 1); STAGE(SB(0, 0), Bt, ldb, boff, bcol, t + 2);
;       BAR; WAIT_L(0); MMA(0, 1, At, B1); BAR;
;       LDA(At, 0, 1); STAGE(SA(0, 0), A, lda, aoff, brow, t + 2);
;       BAR; WAIT_L(0); MMA(1, 0, At, B0); BAR; SCHED;
;       STAGE(SB(0, 1), Bt, ldb, boff, bcol + HALF, t + 2);
;       WAIT_V(6); BAR; MMA(1, 1, At, B1); BAR;
;       LDB(B0, 1, 0); SCHED; LDA(At, 1, 0); STAGE(SA(0, 1), A, lda, aoff, brow + HALF, t + 2);
;       WAIT_L(8); BAR; WAIT_L(0); MMA(0, 0, At, B0); BAR; SCHED;
	s_add_u32 s42, s8, s14
	ds_read_b128 v[214:217], v185
	ds_read_b128 v[218:221], v185 offset:1024
	ds_read_b128 v[234:237], v185 offset:2048
	ds_read_b128 v[238:241], v185 offset:3072
	s_addc_u32 s43, s9, s15
	s_mov_b32 m0, s24
	s_add_u32 s98, s42, s34
	s_addc_u32 s99, s43, s35
	global_load_lds_dwordx4 v135, s[98:99]
	s_mov_b32 m0, s25
	s_add_u32 s98, s42, s64
	s_addc_u32 s99, s43, s65
	global_load_lds_dwordx4 v135, s[98:99]
	s_waitcnt vmcnt(10)
	s_barrier
	s_waitcnt lgkmcnt(0)
	s_waitcnt lgkmcnt(0)
	v_mfma_f32_16x16x32_bf16 v[94:97], v[214:217], v[168:171], 0
	v_mfma_f32_16x16x32_bf16 v[90:93], v[234:237], v[168:171], 0
	v_mfma_f32_16x16x32_bf16 v[86:89], v[214:217], v[176:179], 0
	v_mfma_f32_16x16x32_bf16 v[82:85], v[234:237], v[176:179], 0
	v_mfma_f32_16x16x32_bf16 v[78:81], v[214:217], v[198:201], 0
	v_mfma_f32_16x16x32_bf16 v[74:77], v[234:237], v[198:201], 0
	v_mfma_f32_16x16x32_bf16 v[70:73], v[214:217], v[206:209], 0
	v_mfma_f32_16x16x32_bf16 v[66:69], v[234:237], v[206:209], 0
	v_mfma_f32_16x16x32_bf16 v[94:97], v[218:221], v[172:175], v[94:97]
	v_mfma_f32_16x16x32_bf16 v[90:93], v[238:241], v[172:175], v[90:93]
	v_mfma_f32_16x16x32_bf16 v[86:89], v[218:221], v[194:197], v[86:89]
	v_mfma_f32_16x16x32_bf16 v[82:85], v[238:241], v[194:197], v[82:85]
	v_mfma_f32_16x16x32_bf16 v[78:81], v[218:221], v[202:205], v[78:81]
	v_mfma_f32_16x16x32_bf16 v[74:77], v[238:241], v[202:205], v[74:77]
	v_mfma_f32_16x16x32_bf16 v[70:73], v[218:221], v[210:213], v[70:73]
	v_mfma_f32_16x16x32_bf16 v[66:69], v[238:241], v[210:213], v[66:69]
	s_barrier
	ds_read_b128 v[168:171], v147 offset:16384
	ds_read_b128 v[172:175], v147 offset:17408
	ds_read_b128 v[176:179], v147 offset:18432
	ds_read_b128 v[194:197], v147 offset:19456
	ds_read_b128 v[198:201], v147 offset:20480
	ds_read_b128 v[202:205], v147 offset:21504
	ds_read_b128 v[206:209], v147 offset:22528
	ds_read_b128 v[210:213], v147 offset:23552
	s_mov_b32 m0, s26
	s_add_u32 s98, s40, s34
	s_addc_u32 s99, s41, s35
	global_load_lds_dwordx4 v135, s[98:99]
	s_mov_b32 m0, s27
	s_add_u32 s98, s40, s64
	s_addc_u32 s99, s41, s65
	global_load_lds_dwordx4 v135, s[98:99]
	s_barrier
	s_waitcnt lgkmcnt(0)
	s_waitcnt lgkmcnt(0)
	v_mfma_f32_16x16x32_bf16 v[62:65], v[152:155], v[168:171], 0
	v_mfma_f32_16x16x32_bf16 v[58:61], v[160:163], v[168:171], 0
	v_mfma_f32_16x16x32_bf16 v[54:57], v[152:155], v[176:179], 0
	v_mfma_f32_16x16x32_bf16 v[50:53], v[160:163], v[176:179], 0
	v_mfma_f32_16x16x32_bf16 v[46:49], v[152:155], v[198:201], 0
	v_mfma_f32_16x16x32_bf16 v[42:45], v[160:163], v[198:201], 0
	v_mfma_f32_16x16x32_bf16 v[38:41], v[152:155], v[206:209], 0
	v_mfma_f32_16x16x32_bf16 v[34:37], v[160:163], v[206:209], 0
	v_mfma_f32_16x16x32_bf16 v[62:65], v[156:159], v[172:175], v[62:65]
	v_mfma_f32_16x16x32_bf16 v[58:61], v[164:167], v[172:175], v[58:61]
	v_mfma_f32_16x16x32_bf16 v[54:57], v[156:159], v[194:197], v[54:57]
	v_mfma_f32_16x16x32_bf16 v[50:53], v[164:167], v[194:197], v[50:53]
	v_mfma_f32_16x16x32_bf16 v[46:49], v[156:159], v[202:205], v[46:49]
	v_mfma_f32_16x16x32_bf16 v[42:45], v[164:167], v[202:205], v[42:45]
	v_mfma_f32_16x16x32_bf16 v[38:41], v[156:159], v[210:213], v[38:41]
	v_mfma_f32_16x16x32_bf16 v[34:37], v[164:167], v[210:213], v[34:37]
	s_barrier
	s_mov_b32 m0, s28
	s_add_u32 s98, s42, s68
	s_addc_u32 s99, s43, s69
	global_load_lds_dwordx4 v135, s[98:99]
	s_mov_b32 m0, s29
	s_add_u32 s98, s42, s70
	s_addc_u32 s99, s43, s71
	global_load_lds_dwordx4 v135, s[98:99]
	s_waitcnt vmcnt(10)
	s_barrier
	v_mfma_f32_16x16x32_bf16 v[30:33], v[214:217], v[168:171], 0
	v_mfma_f32_16x16x32_bf16 v[26:29], v[234:237], v[168:171], 0
	v_mfma_f32_16x16x32_bf16 v[22:25], v[214:217], v[176:179], 0
	v_mfma_f32_16x16x32_bf16 v[18:21], v[234:237], v[176:179], 0
	v_mfma_f32_16x16x32_bf16 v[14:17], v[214:217], v[198:201], 0
	v_mfma_f32_16x16x32_bf16 v[10:13], v[234:237], v[198:201], 0
	v_mfma_f32_16x16x32_bf16 v[6:9], v[214:217], v[206:209], 0
	v_mfma_f32_16x16x32_bf16 v[2:5], v[234:237], v[206:209], 0
	v_mfma_f32_16x16x32_bf16 v[30:33], v[218:221], v[172:175], v[30:33]
	v_mfma_f32_16x16x32_bf16 v[26:29], v[238:241], v[172:175], v[26:29]
	v_mfma_f32_16x16x32_bf16 v[22:25], v[218:221], v[194:197], v[22:25]
	v_mfma_f32_16x16x32_bf16 v[18:21], v[238:241], v[194:197], v[18:21]
	v_mfma_f32_16x16x32_bf16 v[14:17], v[218:221], v[202:205], v[14:17]
	v_mfma_f32_16x16x32_bf16 v[10:13], v[238:241], v[202:205], v[10:13]
	v_mfma_f32_16x16x32_bf16 v[6:9], v[218:221], v[210:213], v[6:9]
	v_mfma_f32_16x16x32_bf16 v[2:5], v[238:241], v[210:213], v[2:5]
	s_barrier
	ds_read_b128 v[152:155], v186
	ds_read_b128 v[156:159], v186 offset:1024
	ds_read_b128 v[160:163], v186 offset:2048
	ds_read_b128 v[164:167], v186 offset:3072
	ds_read_b128 v[168:171], v147 offset:32768
	ds_read_b128 v[172:175], v147 offset:33792
	ds_read_b128 v[176:179], v147 offset:34816
	ds_read_b128 v[194:197], v147 offset:35840
	ds_read_b128 v[198:201], v147 offset:36864
	ds_read_b128 v[202:205], v147 offset:37888
	ds_read_b128 v[206:209], v147 offset:38912
	ds_read_b128 v[210:213], v147 offset:39936
	s_mov_b32 m0, s30
	s_add_u32 s98, s40, s68
	s_addc_u32 s99, s41, s69
	global_load_lds_dwordx4 v135, s[98:99]
	s_mov_b32 m0, s31
	s_add_u32 s98, s40, s70
	s_addc_u32 s99, s41, s71
	global_load_lds_dwordx4 v135, s[98:99]
	s_waitcnt lgkmcnt(8)
	s_waitcnt vmcnt(10)
	s_barrier
; #define LDA(dst, b, h) for (int m = 0; m < 4; ++m) for (int k = 0; k < 2; ++k) \
;     dst[m][k] = *reinterpret_cast<const bf16x8*>((char*)SA(b, h) + a_thr + (m * 2 + k) * 1024)
; #define LDB(dst, b, h) for (int n = 0; n < 2; ++n) for (int k = 0; k < 2; ++k) \
;     dst[n][k] = *reinterpret_cast<const bf16x8*>((char*)SB(b, h) + b_thr + (n * 2 + k) * 1024)
; #define MMA(ai, bj, At, Btf) do { __builtin_amdgcn_s_setprio(1); \
;     for (int m = 0; m < 4; ++m) for (int n = 0; n < 2; ++n) for (int k = 0; k < 2; ++k) \
;       acc[ai][bj][m][n] = __builtin_amdgcn_mfma_f32_16x16x32_bf16(Btf[n][k], At[m][k], acc[ai][bj][m][n], 0, 0, 0); \
;     __builtin_amdgcn_s_setprio(0); } while (0)
; #define WAIT_V(n) asm volatile("s_waitcnt vmcnt(" #n ")" ::: "memory")
; #define WAIT_L(n) asm volatile("s_waitcnt lgkmcnt(" #n ")" ::: "memory")
; #define BAR __builtin_amdgcn_s_barrier()
; #define SCHED __builtin_amdgcn_sched_barrier(0)
; template <bool OVL, bool PANEL = false, class Epi>
; __device__ __forceinline__ void gemm_phase(const bf16_t* __restrict__ A, long lda, const bf16_t* __restrict__ Bt, long ldb, int nM, int nN, int K,
;                                            const Epi& epi, bf16_t* shm, int w0) {
;     ...
;       WAIT_L(8); BAR; WAIT_L(0); MMA(0, 0, At, B0); BAR; SCHED;
;       LDB(B1, 1, 1); STAGE(SB(1, 0), Bt, ldb, boff, bcol, t + 3);
;       BAR; WAIT_L(0); MMA(0, 1, At, B1); BAR;
;       LDA(At, 1, 1); STAGE(SA(1, 0), A, lda, aoff, brow, t + 3);
;       BAR; WAIT_L(0); MMA(1, 0, At, B0); BAR; SCHED;
;       STAGE(SB(1, 1), Bt, ldb, boff, bcol + HALF, t + 3);
;       WAIT_V(6); BAR; MMA(1, 1, At, B1); BAR;
	s_waitcnt lgkmcnt(0)
	s_waitcnt lgkmcnt(0)
	v_mfma_f32_16x16x32_bf16 v[126:129], v[152:155], v[168:171], v[126:129]
	v_mfma_f32_16x16x32_bf16 v[122:125], v[160:163], v[168:171], v[122:125]
	v_mfma_f32_16x16x32_bf16 v[118:121], v[152:155], v[176:179], v[118:121]
	v_mfma_f32_16x16x32_bf16 v[114:117], v[160:163], v[176:179], v[114:117]
	v_mfma_f32_16x16x32_bf16 v[110:113], v[152:155], v[198:201], v[110:113]
	v_mfma_f32_16x16x32_bf16 v[106:109], v[160:163], v[198:201], v[106:109]
	v_mfma_f32_16x16x32_bf16 v[102:105], v[152:155], v[206:209], v[102:105]
	v_mfma_f32_16x16x32_bf16 v[98:101], v[160:163], v[206:209], v[98:101]
	v_mfma_f32_16x16x32_bf16 v[126:129], v[156:159], v[172:175], v[126:129]
	v_mfma_f32_16x16x32_bf16 v[122:125], v[164:167], v[172:175], v[122:125]
	v_mfma_f32_16x16x32_bf16 v[118:121], v[156:159], v[194:197], v[118:121]
	v_mfma_f32_16x16x32_bf16 v[114:117], v[164:167], v[194:197], v[114:117]
	v_mfma_f32_16x16x32_bf16 v[110:113], v[156:159], v[202:205], v[110:113]
	v_mfma_f32_16x16x32_bf16 v[106:109], v[164:167], v[202:205], v[106:109]
	v_mfma_f32_16x16x32_bf16 v[102:105], v[156:159], v[210:213], v[102:105]
	v_mfma_f32_16x16x32_bf16 v[98:101], v[164:167], v[210:213], v[98:101]
	s_barrier
	ds_read_b128 v[214:217], v187
	ds_read_b128 v[218:221], v187 offset:1024
	ds_read_b128 v[234:237], v187 offset:2048
	ds_read_b128 v[238:241], v187 offset:3072
	s_mov_b32 m0, s32
	s_add_u32 s98, s42, s94
	s_addc_u32 s99, s43, s95
	global_load_lds_dwordx4 v135, s[98:99]
	s_mov_b32 m0, s44
	s_add_u32 s98, s42, s72
	s_addc_u32 s99, s43, s73
	global_load_lds_dwordx4 v135, s[98:99]
	s_waitcnt vmcnt(10)
	s_barrier
	s_waitcnt lgkmcnt(0)
	s_waitcnt lgkmcnt(0)
	v_mfma_f32_16x16x32_bf16 v[94:97], v[214:217], v[168:171], v[94:97]
	v_mfma_f32_16x16x32_bf16 v[90:93], v[234:237], v[168:171], v[90:93]
	v_mfma_f32_16x16x32_bf16 v[86:89], v[214:217], v[176:179], v[86:89]
	v_mfma_f32_16x16x32_bf16 v[82:85], v[234:237], v[176:179], v[82:85]
	v_mfma_f32_16x16x32_bf16 v[78:81], v[214:217], v[198:201], v[78:81]
	v_mfma_f32_16x16x32_bf16 v[74:77], v[234:237], v[198:201], v[74:77]
	v_mfma_f32_16x16x32_bf16 v[70:73], v[214:217], v[206:209], v[70:73]
	v_mfma_f32_16x16x32_bf16 v[66:69], v[234:237], v[206:209], v[66:69]
	v_mfma_f32_16x16x32_bf16 v[94:97], v[218:221], v[172:175], v[94:97]
	v_mfma_f32_16x16x32_bf16 v[90:93], v[238:241], v[172:175], v[90:93]
	v_mfma_f32_16x16x32_bf16 v[86:89], v[218:221], v[194:197], v[86:89]
	v_mfma_f32_16x16x32_bf16 v[82:85], v[238:241], v[194:197], v[82:85]
	v_mfma_f32_16x16x32_bf16 v[78:81], v[218:221], v[202:205], v[78:81]
	v_mfma_f32_16x16x32_bf16 v[74:77], v[238:241], v[202:205], v[74:77]
	v_mfma_f32_16x16x32_bf16 v[70:73], v[218:221], v[210:213], v[70:73]
	v_mfma_f32_16x16x32_bf16 v[66:69], v[238:241], v[210:213], v[66:69]
	s_barrier
	ds_read_b128 v[168:171], v147 offset:49152
	ds_read_b128 v[172:175], v147 offset:50176
	ds_read_b128 v[176:179], v147 offset:51200
	ds_read_b128 v[194:197], v147 offset:52224
	ds_read_b128 v[198:201], v147 offset:53248
	ds_read_b128 v[202:205], v147 offset:54272
	ds_read_b128 v[206:209], v147 offset:55296
	ds_read_b128 v[210:213], v147 offset:56320
	s_mov_b32 m0, s45
	s_add_u32 s98, s40, s94
	s_addc_u32 s99, s41, s95
	global_load_lds_dwordx4 v135, s[98:99]
	s_mov_b32 m0, s46
	s_add_u32 s98, s40, s72
	s_addc_u32 s99, s41, s73
	global_load_lds_dwordx4 v135, s[98:99]
	s_barrier
	s_waitcnt lgkmcnt(0)
	s_waitcnt lgkmcnt(0)
	v_mfma_f32_16x16x32_bf16 v[62:65], v[152:155], v[168:171], v[62:65]
	v_mfma_f32_16x16x32_bf16 v[58:61], v[160:163], v[168:171], v[58:61]
	v_mfma_f32_16x16x32_bf16 v[54:57], v[152:155], v[176:179], v[54:57]
	v_mfma_f32_16x16x32_bf16 v[50:53], v[160:163], v[176:179], v[50:53]
	v_mfma_f32_16x16x32_bf16 v[46:49], v[152:155], v[198:201], v[46:49]
	v_mfma_f32_16x16x32_bf16 v[42:45], v[160:163], v[198:201], v[42:45]
	v_mfma_f32_16x16x32_bf16 v[38:41], v[152:155], v[206:209], v[38:41]
	v_mfma_f32_16x16x32_bf16 v[34:37], v[160:163], v[206:209], v[34:37]
	v_mfma_f32_16x16x32_bf16 v[62:65], v[156:159], v[172:175], v[62:65]
	v_mfma_f32_16x16x32_bf16 v[58:61], v[164:167], v[172:175], v[58:61]
	v_mfma_f32_16x16x32_bf16 v[54:57], v[156:159], v[194:197], v[54:57]
	v_mfma_f32_16x16x32_bf16 v[50:53], v[164:167], v[194:197], v[50:53]
	v_mfma_f32_16x16x32_bf16 v[46:49], v[156:159], v[202:205], v[46:49]
	v_mfma_f32_16x16x32_bf16 v[42:45], v[164:167], v[202:205], v[42:45]
	v_mfma_f32_16x16x32_bf16 v[38:41], v[156:159], v[210:213], v[38:41]
	v_mfma_f32_16x16x32_bf16 v[34:37], v[164:167], v[210:213], v[34:37]
	s_barrier
	s_mov_b32 m0, s47
	s_add_u32 s98, s42, s18
	s_addc_u32 s99, s43, s19
	global_load_lds_dwordx4 v135, s[98:99]
	s_mov_b32 m0, s48
	s_add_u32 s98, s42, s20
	s_addc_u32 s99, s43, s21
	global_load_lds_dwordx4 v135, s[98:99]
	s_add_i32 s1, s1, 2
	s_add_u32 s14, s14, 0x100
	s_addc_u32 s15, s15, 0
	s_cmp_lt_u32 s1, 12
	s_waitcnt vmcnt(10)
	s_barrier
	v_mfma_f32_16x16x32_bf16 v[30:33], v[214:217], v[168:171], v[30:33]
	v_mfma_f32_16x16x32_bf16 v[26:29], v[234:237], v[168:171], v[26:29]
	v_mfma_f32_16x16x32_bf16 v[22:25], v[214:217], v[176:179], v[22:25]
	v_mfma_f32_16x16x32_bf16 v[18:21], v[234:237], v[176:179], v[18:21]
	v_mfma_f32_16x16x32_bf16 v[14:17], v[214:217], v[198:201], v[14:17]
	v_mfma_f32_16x16x32_bf16 v[10:13], v[234:237], v[198:201], v[10:13]
	v_mfma_f32_16x16x32_bf16 v[6:9], v[214:217], v[206:209], v[6:9]
	v_mfma_f32_16x16x32_bf16 v[2:5], v[234:237], v[206:209], v[2:5]
	v_mfma_f32_16x16x32_bf16 v[30:33], v[218:221], v[172:175], v[30:33]
	v_mfma_f32_16x16x32_bf16 v[26:29], v[238:241], v[172:175], v[26:29]
	v_mfma_f32_16x16x32_bf16 v[22:25], v[218:221], v[194:197], v[22:25]
	v_mfma_f32_16x16x32_bf16 v[18:21], v[238:241], v[194:197], v[18:21]
	v_mfma_f32_16x16x32_bf16 v[14:17], v[218:221], v[202:205], v[14:17]
	v_mfma_f32_16x16x32_bf16 v[10:13], v[238:241], v[202:205], v[10:13]
	v_mfma_f32_16x16x32_bf16 v[6:9], v[218:221], v[210:213], v[6:9]
	v_mfma_f32_16x16x32_bf16 v[2:5], v[238:241], v[210:213], v[2:5]
	s_barrier
